# stack9: expert-table u-int8/v-fp8 conversion moved from attention phase into waves 4-7 idle time during PEER top-k stage 1
# speedup vs baseline: 1.0437x; 1.0088x over previous
; template <int D>
; DI void attn_task2(const u16* __restrict__ qb, const u16* __restrict__ kd, const u16* __restrict__ vTd, const int b, const int h,
;                    const int rA, const int l0A, const int rB, const int l0B, const float c2, f32x4 (&O)[2][4], float (&m_out)[2], float (&l_out)[2]) {
;     ...
;   const float c1 = 0.125f * LOG2E;
;   const float c2d = c2 * (float)D;
;   int nsteps = (l0A + 16 + 31) >> 5;
;   nsteps = nsteps > 5 ? 5 : nsteps;
;   int l0[2] = {l0A, l0B}, lq[2], first[2], bhr[2];
;   bf16x8 qf[2][2];
;   float m[2] = {-1e30f, -1e30f}, l[2] = {0.f, 0.f};
; #pragma unroll
;   for (int z = 0; z < 2; ++z) {
;     const int r = z ? rB : rA;
;     lq[z] = l0[z] + i16;
;     const int tq = D * lq[z] + r;
; #pragma unroll
;     for (int kk = 0; kk < 2; ++kk) qf[z][kk] = *(const bf16x8*)(qb + (size_t)(b * SEQ + tq) * 512 + h * 64 + 8 * g + 32 * kk);
; #pragma unroll
;     for (int c = 0; c < 4; ++c) O[z][c] = f32x4{0.f, 0.f, 0.f, 0.f};
;     first[z] = l0[z] + 16 - 32 * nsteps;
;     bhr[z] = ((b * 8 + h) * D + r) * (128 / D);
;   }
;   bf16x8 kf[2][2][2], vf[2][4];
; DI void phase_attn(const Params& p, char* smem) {
;     ...
;     const int qblk = 7 - (item >> 7), bh = item & 127, b = bh >> 3, h = bh & 7;
;     const int t0 = qblk * 256;
;     const float c2 = exp2f(-(float)(h + 1)) * LOG2E;
;     {
;       f32x4 O[2][4]; float m[2], l[2];
;       attn_task2<1>(qb, kb, vT1, b, h, 0, t0 + 32 * w, 0, t0 + 32 * w + 16, c2, O, m, l);
.LBB0_154:
	s_lshl_b32 s0, s82, 1
	s_and_b32 s4, s82, 7
	s_and_b32 s0, s0, 0xffffff00
	s_sub_i32 s50, 0x700, s0
	s_add_i32 s0, s4, 1
	v_cvt_f32_ubyte0_e32 v1, s0
	s_mov_b32 s0, 0x42fc0000
	v_cmp_lt_f32_e32 vcc, s0, v1
	s_and_b32 s20, s95, 0xffffff00
	s_bfe_u32 s83, s82, 0x40003
	v_cndmask_b32_e32 v2, 0, v209, vcc
	v_sub_f32_e32 v1, v2, v1
	v_exp_f32_e32 v1, v1
	s_and_b64 s[0:1], vcc, exec
	s_cselect_b32 s0, 0xffffffc0, 0
	s_add_i32 s1, s50, s57
	v_ldexp_f32 v1, v1, s0
	s_add_i32 s0, s1, 47
	s_ashr_i32 s0, s0, 5
	s_lshl_b32 s51, s83, 11
	s_lshl_b32 s42, s4, 7
	v_mov_b32_e32 v29, 0
	v_mul_f32_e32 v145, 0x3fb8aa3b, v1
	s_cmp_lt_i32 s0, 1
	v_lshl_add_u64 v[146:147], v[116:117], 0, s[42:43]
	s_cbranch_scc1 .LBB0_184
	v_or_b32_e32 v148, s1, v168
	v_add_u32_e32 v2, s51, v148
	v_ashrrev_i32_e32 v3, 31, v2
	v_lshlrev_b64 v[2:3], 10, v[2:3]
	v_lshl_add_u64 v[2:3], v[146:147], 0, v[2:3]
	v_add_u32_e32 v4, s1, v168
	global_load_dwordx4 v[50:53], v[2:3], off
	global_load_dwordx4 v[54:57], v[2:3], off offset:64
	v_add3_u32 v2, v4, s51, 16
	v_ashrrev_i32_e32 v3, 31, v2
	v_lshlrev_b64 v[2:3], 10, v[2:3]
	v_lshl_add_u64 v[2:3], v[146:147], 0, v[2:3]
	global_load_dwordx4 v[58:61], v[2:3], off
	global_load_dwordx4 v[62:65], v[2:3], off offset:64
	s_min_i32 s5, s0, 5
	s_lshl_b32 s0, s83, 10
	s_or_b32 s21, s0, s42
	s_lshl_b32 s0, s5, 5
	s_sub_i32 s22, s0, 47
	s_sub_i32 s0, s57, s0
	v_mov_b32_e32 v151, 0
	v_add_u32_e32 v1, 12, v4
	v_add_u32_e32 v150, 13, v4
	v_add_u32_e32 v141, 10, v4
	v_add_u32_e32 v152, 11, v4
	v_mov_b32_e32 v154, v145
	v_mov_b32_e32 v155, v145
	v_mov_b32_e32 v149, v148
	s_sub_i32 s23, s0, s20
	v_mov_b32_e32 v216, 0xf149f2ca
	v_mov_b32_e32 v153, 0
	v_mov_b32_e32 v215, 0xf149f2ca
	v_mov_b32_e32 v26, 0
	v_mov_b32_e32 v27, v151
	v_mov_b32_e32 v28, v151
	v_mov_b32_e32 v29, v151
	v_mov_b32_e32 v18, 0
	v_mov_b32_e32 v19, v151
	v_mov_b32_e32 v20, v151
	v_mov_b32_e32 v21, v151
	v_mov_b32_e32 v22, 0
	v_mov_b32_e32 v23, v151
	v_mov_b32_e32 v24, v151
	v_mov_b32_e32 v25, v151
	v_mov_b32_e32 v30, 0
	v_mov_b32_e32 v31, v151
	v_mov_b32_e32 v32, v151
	v_mov_b32_e32 v33, v151
	v_mov_b32_e32 v34, 0
	v_mov_b32_e32 v35, v151
	v_mov_b32_e32 v36, v151
	v_mov_b32_e32 v37, v151
	v_mov_b32_e32 v38, 0
	v_mov_b32_e32 v39, v151
	v_mov_b32_e32 v40, v151
	v_mov_b32_e32 v41, v151
	v_mov_b32_e32 v42, 0
	v_mov_b32_e32 v43, v151
	v_mov_b32_e32 v44, v151
	v_mov_b32_e32 v45, v151
	v_mov_b32_e32 v46, 0
	v_mov_b32_e32 v47, v151
	v_mov_b32_e32 v48, v151
	v_mov_b32_e32 v49, v151

; DI unsigned pk4_i8(float a, float b, float c, float d) {
;   const int ia = (int)rintf(a), ib = (int)rintf(b), ic = (int)rintf(c), id = (int)rintf(d);
;   return (unsigned)(ia & 255) | ((unsigned)(ib & 255) << 8) | ((unsigned)(ic & 255) << 16) | ((unsigned)(id & 255) << 24);
; }
; DI void cvt_rows_i8(const float* __restrict__ src, unsigned char* __restrict__ dst, float* __restrict__ scale_out, size_t n16, size_t gtid, size_t gsz) {
;   for (size_t i = gtid; i < n16; i += gsz) {
;     const float4 a = *(const float4*)(src + i * 16), b = *(const float4*)(src + i * 16 + 4), c = *(const float4*)(src + i * 16 + 8), d = *(const float4*)(src + i * 16 + 12);
;     float m = fmaxf(fmaxf(fmaxf(fabsf(a.x), fabsf(a.y)), fmaxf(fabsf(a.z), fabsf(a.w))), fmaxf(fmaxf(fabsf(b.x), fabsf(b.y)), fmaxf(fabsf(b.z), fabsf(b.w))));
;     m = fmaxf(m, fmaxf(fmaxf(fmaxf(fabsf(c.x), fabsf(c.y)), fmaxf(fabsf(c.z), fabsf(c.w))), fmaxf(fmaxf(fabsf(d.x), fabsf(d.y)), fmaxf(fabsf(d.z), fabsf(d.w)))));
; #pragma unroll
;     for (int o = 32; o > 0; o >>= 1) m = fmaxf(m, __shfl_xor(m, o, 64));
;     m = fmaxf(m, 1e-30f);
;     const float q = 127.f / m;
;     uint4 r;
;     r.x = pk4_i8(a.x * q, a.y * q, a.z * q, a.w * q); r.y = pk4_i8(b.x * q, b.y * q, b.z * q, b.w * q);
;     r.z = pk4_i8(c.x * q, c.y * q, c.z * q, c.w * q); r.w = pk4_i8(d.x * q, d.y * q, d.z * q, d.w * q);
.LBB0_407:
	s_or_b64 exec, exec, s[62:63]
	v_readfirstlane_b32 s92, v0
	s_nop 3
	s_lshr_b32 s92, s92, 6
	s_cmp_lt_u32 s92, 4
	s_cbranch_scc1 .Lmy_cv_done
	s_sub_u32 s92, s92, 4
	s_lshl_b32 s93, s77, 2
	s_add_u32 s93, s93, s92
	v_readlane_b32 s98, v239, 10
	v_readlane_b32 s99, v239, 11
	v_readlane_b32 s100, v239, 12
	v_readlane_b32 s101, v239, 13
	v_mbcnt_lo_u32_b32 v224, -1, 0
	v_mbcnt_hi_u32_b32 v224, -1, v224
	v_xor_b32_e32 v218, 32, v224
	v_lshlrev_b32_e32 v218, 2, v218
	v_xor_b32_e32 v219, 16, v224
	v_lshlrev_b32_e32 v219, 2, v219
	v_xor_b32_e32 v220, 8, v224
	v_lshlrev_b32_e32 v220, 2, v220
	v_xor_b32_e32 v221, 4, v224
	v_lshlrev_b32_e32 v221, 2, v221
	v_xor_b32_e32 v222, 2, v224
	v_lshlrev_b32_e32 v222, 2, v222
	v_xor_b32_e32 v223, 1, v224
	v_lshlrev_b32_e32 v223, 2, v223
	v_lshlrev_b32_e32 v225, 6, v224
	v_lshlrev_b32_e32 v226, 4, v224
	v_cmp_eq_u32_e64 s[90:91], 0, v224
	s_mov_b32 s97, 0x42fe0000
	s_mov_b32 s89, s93
	s_lshl_b32 s88, s89, 12
	s_add_u32 s86, s98, s88
	s_addc_u32 s87, s99, 0
	global_load_dwordx4 v[202:205], v225, s[86:87] nt
	global_load_dwordx4 v[206:209], v225, s[86:87] offset:16 nt
	global_load_dwordx4 v[210:213], v225, s[86:87] offset:32 nt
	global_load_dwordx4 v[214:217], v225, s[86:87] offset:48 nt
	s_add_u32 s89, s93, 8192
	s_lshl_b32 s88, s89, 12
	s_add_u32 s86, s98, s88
	s_addc_u32 s87, s99, 0
	global_load_dwordx4 v[240:243], v225, s[86:87] nt
	global_load_dwordx4 v[244:247], v225, s[86:87] offset:16 nt
	global_load_dwordx4 v[248:251], v225, s[86:87] offset:32 nt
	global_load_dwordx4 v[252:255], v225, s[86:87] offset:48 nt
	s_mov_b32 s96, 0xda24260
	s_waitcnt vmcnt(4)
	v_max_f32_e64 v185, |v205|, |v205|
	v_max_f32_e64 v186, |v204|, |v204|
	v_max_f32_e64 v187, |v209|, |v209|
	v_max_f32_e64 v188, |v208|, |v208|
	v_max_f32_e64 v189, |v211|, |v211|
	v_max_f32_e64 v190, |v210|, |v210|
	v_max_f32_e64 v193, |v217|, |v217|
	v_max_f32_e64 v194, |v216|, |v216|
	v_max_f32_e64 v191, |v213|, |v213|
	v_max_f32_e64 v192, |v212|, |v212|
	v_max_f32_e32 v185, v186, v185
	v_max_f32_e32 v186, v188, v187
	v_max_f32_e32 v187, v190, v189
	v_max_f32_e32 v189, v194, v193
	v_max_f32_e32 v188, v192, v191
	v_max3_f32 v189, |v214|, |v215|, v189
	v_max3_f32 v185, |v202|, |v203|, v185
	v_max3_f32 v186, |v206|, |v207|, v186
	v_max3_f32 v187, v187, v188, v189
	v_max3_f32 v185, v185, v186, v187
	ds_bpermute_b32 v186, v218, v185
	s_waitcnt lgkmcnt(0)
	v_max_f32_e32 v186, v186, v186
	v_max_f32_e32 v185, v185, v186
	ds_bpermute_b32 v186, v219, v185
	s_waitcnt lgkmcnt(0)
	v_max_f32_e32 v186, v186, v186
	v_max_f32_e32 v185, v185, v186
	ds_bpermute_b32 v186, v220, v185
	s_waitcnt lgkmcnt(0)
	v_max_f32_e32 v186, v186, v186
	v_max_f32_e32 v185, v185, v186
	ds_bpermute_b32 v186, v221, v185
	s_waitcnt lgkmcnt(0)
	v_max_f32_e32 v186, v186, v186
	v_max_f32_e32 v185, v185, v186
	ds_bpermute_b32 v186, v222, v185
	s_waitcnt lgkmcnt(0)
	v_max_f32_e32 v186, v186, v186
	v_max_f32_e32 v185, v185, v186
	ds_bpermute_b32 v186, v223, v185
	s_waitcnt lgkmcnt(0)
	v_max3_f32 v185, v185, v186, s96
	v_div_scale_f32 v186, s[94:95], v185, v185, s97
	v_rcp_f32_e32 v187, v186
	v_div_scale_f32 v188, vcc, s97, v185, s97
	v_fma_f32 v189, -v186, v187, 1.0
	v_fmac_f32_e32 v187, v189, v187
	v_mul_f32_e32 v189, v188, v187
	v_fma_f32 v190, -v186, v189, v188
	v_fmac_f32_e32 v189, v190, v187
	v_fma_f32 v186, -v186, v189, v188
	v_div_fmas_f32 v186, v186, v187, v189
	v_div_fixup_f32 v186, v186, v185, s97
	v_mul_f32_e32 v202, v202, v186
	v_mul_f32_e32 v203, v203, v186
	v_mul_f32_e32 v205, v205, v186
	v_mul_f32_e32 v206, v206, v186
	v_mul_f32_e32 v207, v207, v186
	v_mul_f32_e32 v209, v209, v186
	v_mul_f32_e32 v211, v211, v186
	v_mul_f32_e32 v215, v215, v186
	v_mul_f32_e32 v210, v210, v186
	v_mul_f32_e32 v213, v213, v186
	v_mul_f32_e32 v214, v214, v186
	v_mul_f32_e32 v217, v217, v186
	v_rndne_f32_e32 v202, v202
	v_rndne_f32_e32 v203, v203
	v_rndne_f32_e32 v205, v205
	v_rndne_f32_e32 v206, v206
	v_rndne_f32_e32 v207, v207
	v_rndne_f32_e32 v209, v209
	v_rndne_f32_e32 v211, v211
	v_rndne_f32_e32 v215, v215
	v_mul_f32_e32 v204, v204, v186
	v_mul_f32_e32 v208, v208, v186
	v_mul_f32_e32 v212, v212, v186
	v_mul_f32_e32 v216, v216, v186
	v_rndne_f32_e32 v210, v210
	v_rndne_f32_e32 v213, v213
	v_rndne_f32_e32 v214, v214
	v_rndne_f32_e32 v217, v217
	v_cvt_i32_f32_e32 v206, v206
	v_cvt_i32_f32_e32 v202, v202
	v_cvt_i32_f32_e32 v203, v203
	v_cvt_i32_f32_e32 v207, v207
	v_cvt_i32_f32_sdwa v205, v205 dst_sel:BYTE_3 dst_unused:UNUSED_PAD src0_sel:DWORD
	v_cvt_i32_f32_sdwa v209, v209 dst_sel:BYTE_3 dst_unused:UNUSED_PAD src0_sel:DWORD
	v_cvt_i32_f32_e32 v211, v211
	v_cvt_i32_f32_e32 v215, v215
	v_rndne_f32_e32 v204, v204
	v_rndne_f32_e32 v208, v208
	v_rndne_f32_e32 v212, v212
	v_rndne_f32_e32 v216, v216
	v_cvt_i32_f32_e32 v214, v214
	v_cvt_i32_f32_e32 v210, v210
	v_cvt_i32_f32_sdwa v213, v213 dst_sel:BYTE_3 dst_unused:UNUSED_PAD src0_sel:DWORD
	v_cvt_i32_f32_sdwa v217, v217 dst_sel:BYTE_3 dst_unused:UNUSED_PAD src0_sel:DWORD
	v_cvt_i32_f32_sdwa v204, v204 dst_sel:WORD_1 dst_unused:UNUSED_PAD src0_sel:DWORD
	v_cvt_i32_f32_sdwa v208, v208 dst_sel:WORD_1 dst_unused:UNUSED_PAD src0_sel:DWORD
	v_cvt_i32_f32_sdwa v212, v212 dst_sel:WORD_1 dst_unused:UNUSED_PAD src0_sel:DWORD
	v_cvt_i32_f32_sdwa v216, v216 dst_sel:WORD_1 dst_unused:UNUSED_PAD src0_sel:DWORD
	v_lshlrev_b32_e32 v207, 8, v207
	v_lshlrev_b32_e32 v203, 8, v203
	v_or_b32_sdwa v206, v209, v206 dst_sel:DWORD dst_unused:UNUSED_PAD src0_sel:DWORD src1_sel:BYTE_0
	v_or_b32_sdwa v202, v205, v202 dst_sel:DWORD dst_unused:UNUSED_PAD src0_sel:DWORD src1_sel:BYTE_0
	v_lshlrev_b32_e32 v205, 8, v215
	v_lshlrev_b32_e32 v209, 8, v211
; DI void cvt_linear_fp8(const float* __restrict__ src, unsigned char* __restrict__ dst, size_t n16, float scale, size_t gtid, size_t gsz) {
;   for (size_t i = gtid; i < n16; i += gsz) {
;     const float4 a = *(const float4*)(src + i * 16), b = *(const float4*)(src + i * 16 + 4), c = *(const float4*)(src + i * 16 + 8), d = *(const float4*)(src + i * 16 + 12);
; DI unsigned pk4_i8(float a, float b, float c, float d) {
;   const int ia = (int)rintf(a), ib = (int)rintf(b), ic = (int)rintf(c), id = (int)rintf(d);
;   return (unsigned)(ia & 255) | ((unsigned)(ib & 255) << 8) | ((unsigned)(ic & 255) << 16) | ((unsigned)(id & 255) << 24);
; }
; DI void cvt_rows_i8(const float* __restrict__ src, unsigned char* __restrict__ dst, float* __restrict__ scale_out, size_t n16, size_t gtid, size_t gsz) {
;   for (size_t i = gtid; i < n16; i += gsz) {
;     const float4 a = *(const float4*)(src + i * 16), b = *(const float4*)(src + i * 16 + 4), c = *(const float4*)(src + i * 16 + 8), d = *(const float4*)(src + i * 16 + 12);
;     float m = fmaxf(fmaxf(fmaxf(fabsf(a.x), fabsf(a.y)), fmaxf(fabsf(a.z), fabsf(a.w))), fmaxf(fmaxf(fabsf(b.x), fabsf(b.y)), fmaxf(fabsf(b.z), fabsf(b.w))));
;     m = fmaxf(m, fmaxf(fmaxf(fmaxf(fabsf(c.x), fabsf(c.y)), fmaxf(fabsf(c.z), fabsf(c.w))), fmaxf(fmaxf(fabsf(d.x), fabsf(d.y)), fmaxf(fabsf(d.z), fabsf(d.w)))));
; #pragma unroll
;     for (int o = 32; o > 0; o >>= 1) m = fmaxf(m, __shfl_xor(m, o, 64));
;     m = fmaxf(m, 1e-30f);
;     const float q = 127.f / m;
;     uint4 r;
;     r.x = pk4_i8(a.x * q, a.y * q, a.z * q, a.w * q); r.y = pk4_i8(b.x * q, b.y * q, b.z * q, b.w * q);
;     r.z = pk4_i8(c.x * q, c.y * q, c.z * q, c.w * q); r.w = pk4_i8(d.x * q, d.y * q, d.z * q, d.w * q);
;     *(uint4*)(dst + i * 16) = r;
;     if ((i & 63) == 0) scale_out[i >> 6] = m * (1.f / 127.f);
	v_or_b32_sdwa v214, v217, v214 dst_sel:DWORD dst_unused:UNUSED_PAD src0_sel:DWORD src1_sel:BYTE_0
	v_or_b32_sdwa v210, v213, v210 dst_sel:DWORD dst_unused:UNUSED_PAD src0_sel:DWORD src1_sel:BYTE_0
	v_and_b32_e32 v207, 0xff00, v207
	v_and_b32_e32 v203, 0xff00, v203
	v_and_b32_e32 v205, 0xff00, v205
	v_and_b32_e32 v209, 0xff00, v209
	v_and_b32_e32 v208, 0xff0000, v208
	v_and_b32_e32 v204, 0xff0000, v204
	v_and_b32_e32 v211, 0xff0000, v216
	v_and_b32_e32 v212, 0xff0000, v212
	v_or_b32_e32 v206, v206, v207
	v_or_b32_e32 v202, v202, v203
	v_or_b32_e32 v205, v214, v205
	v_or_b32_e32 v207, v210, v209
	v_or_b32_e32 v203, v206, v208
	v_or_b32_e32 v202, v202, v204
	v_or_b32_e32 v205, v205, v211
	v_or_b32_e32 v204, v207, v212
	s_mov_b32 s89, s93
	s_lshl_b32 s88, s89, 10
	s_add_u32 s86, s72, s88
	s_addc_u32 s87, s73, 0
	s_add_u32 s86, s86, 0x4c00000
	s_addc_u32 s87, s87, 0
	global_store_dwordx4 v226, v[202:205], s[86:87]
	v_mul_f32_e32 v185, 0x3c010204, v185
	s_lshl_b32 s88, s89, 2
	s_add_u32 s86, s72, s88
	s_addc_u32 s87, s73, 0
	s_add_u32 s86, s86, 0x1ec01000
	s_addc_u32 s87, s87, 0
	v_mov_b32_e32 v227, 0
	s_mov_b64 exec, s[90:91]
	global_store_dword v227, v185, s[86:87]
	s_mov_b64 exec, -1
	s_mov_b32 s89, s93
	s_lshl_b32 s88, s89, 12
	s_add_u32 s86, s100, s88
	s_addc_u32 s87, s101, 0
	global_load_dwordx4 v[202:205], v225, s[86:87] nt
	global_load_dwordx4 v[206:209], v225, s[86:87] offset:16 nt
	global_load_dwordx4 v[210:213], v225, s[86:87] offset:32 nt
	global_load_dwordx4 v[214:217], v225, s[86:87] offset:48 nt
	s_mov_b32 s96, 0xda24260
	s_waitcnt vmcnt(6)
	v_max_f32_e64 v185, |v243|, |v243|
	v_max_f32_e64 v186, |v242|, |v242|
	v_max_f32_e64 v187, |v247|, |v247|
	v_max_f32_e64 v188, |v246|, |v246|
	v_max_f32_e64 v189, |v249|, |v249|
	v_max_f32_e64 v190, |v248|, |v248|
	v_max_f32_e64 v193, |v255|, |v255|
	v_max_f32_e64 v194, |v254|, |v254|
	v_max_f32_e64 v191, |v251|, |v251|
	v_max_f32_e64 v192, |v250|, |v250|
	v_max_f32_e32 v185, v186, v185
	v_max_f32_e32 v186, v188, v187
	v_max_f32_e32 v187, v190, v189
	v_max_f32_e32 v189, v194, v193
	v_max_f32_e32 v188, v192, v191
	v_max3_f32 v189, |v252|, |v253|, v189
	v_max3_f32 v185, |v240|, |v241|, v185
	v_max3_f32 v186, |v244|, |v245|, v186
	v_max3_f32 v187, v187, v188, v189
	v_max3_f32 v185, v185, v186, v187
	ds_bpermute_b32 v186, v218, v185
	s_waitcnt lgkmcnt(0)
	v_max_f32_e32 v186, v186, v186
	v_max_f32_e32 v185, v185, v186
	ds_bpermute_b32 v186, v219, v185
	s_waitcnt lgkmcnt(0)
	v_max_f32_e32 v186, v186, v186
	v_max_f32_e32 v185, v185, v186
	ds_bpermute_b32 v186, v220, v185
	s_waitcnt lgkmcnt(0)
	v_max_f32_e32 v186, v186, v186
	v_max_f32_e32 v185, v185, v186
	ds_bpermute_b32 v186, v221, v185
	s_waitcnt lgkmcnt(0)
	v_max_f32_e32 v186, v186, v186
	v_max_f32_e32 v185, v185, v186
	ds_bpermute_b32 v186, v222, v185
	s_waitcnt lgkmcnt(0)
	v_max_f32_e32 v186, v186, v186
	v_max_f32_e32 v185, v185, v186
	ds_bpermute_b32 v186, v223, v185
	s_waitcnt lgkmcnt(0)
	v_max3_f32 v185, v185, v186, s96
	v_div_scale_f32 v186, s[94:95], v185, v185, s97
	v_rcp_f32_e32 v187, v186
	v_div_scale_f32 v188, vcc, s97, v185, s97
	v_fma_f32 v189, -v186, v187, 1.0
	v_fmac_f32_e32 v187, v189, v187
	v_mul_f32_e32 v189, v188, v187
	v_fma_f32 v190, -v186, v189, v188
	v_fmac_f32_e32 v189, v190, v187
	v_fma_f32 v186, -v186, v189, v188
	v_div_fmas_f32 v186, v186, v187, v189
	v_div_fixup_f32 v186, v186, v185, s97
	v_mul_f32_e32 v240, v240, v186
	v_mul_f32_e32 v241, v241, v186
	v_mul_f32_e32 v243, v243, v186
	v_mul_f32_e32 v244, v244, v186
	v_mul_f32_e32 v245, v245, v186
	v_mul_f32_e32 v247, v247, v186
	v_mul_f32_e32 v249, v249, v186
	v_mul_f32_e32 v253, v253, v186
	v_mul_f32_e32 v248, v248, v186
	v_mul_f32_e32 v251, v251, v186
	v_mul_f32_e32 v252, v252, v186
	v_mul_f32_e32 v255, v255, v186
	v_rndne_f32_e32 v240, v240
	v_rndne_f32_e32 v241, v241
	v_rndne_f32_e32 v243, v243
	v_rndne_f32_e32 v244, v244
	v_rndne_f32_e32 v245, v245
	v_rndne_f32_e32 v247, v247
	v_rndne_f32_e32 v249, v249
	v_rndne_f32_e32 v253, v253
	v_mul_f32_e32 v242, v242, v186
	v_mul_f32_e32 v246, v246, v186
	v_mul_f32_e32 v250, v250, v186
	v_mul_f32_e32 v254, v254, v186
	v_rndne_f32_e32 v248, v248
	v_rndne_f32_e32 v251, v251
	v_rndne_f32_e32 v252, v252
	v_rndne_f32_e32 v255, v255
	v_cvt_i32_f32_e32 v244, v244
	v_cvt_i32_f32_e32 v240, v240
	v_cvt_i32_f32_e32 v241, v241
	v_cvt_i32_f32_e32 v245, v245
	v_cvt_i32_f32_sdwa v243, v243 dst_sel:BYTE_3 dst_unused:UNUSED_PAD src0_sel:DWORD
	v_cvt_i32_f32_sdwa v247, v247 dst_sel:BYTE_3 dst_unused:UNUSED_PAD src0_sel:DWORD
	v_cvt_i32_f32_e32 v249, v249
	v_cvt_i32_f32_e32 v253, v253
	v_rndne_f32_e32 v242, v242
	v_rndne_f32_e32 v246, v246
	v_rndne_f32_e32 v250, v250
	v_rndne_f32_e32 v254, v254
	v_cvt_i32_f32_e32 v252, v252
	v_cvt_i32_f32_e32 v248, v248
	v_cvt_i32_f32_sdwa v251, v251 dst_sel:BYTE_3 dst_unused:UNUSED_PAD src0_sel:DWORD
	v_cvt_i32_f32_sdwa v255, v255 dst_sel:BYTE_3 dst_unused:UNUSED_PAD src0_sel:DWORD
	v_cvt_i32_f32_sdwa v242, v242 dst_sel:WORD_1 dst_unused:UNUSED_PAD src0_sel:DWORD
	v_cvt_i32_f32_sdwa v246, v246 dst_sel:WORD_1 dst_unused:UNUSED_PAD src0_sel:DWORD
	v_cvt_i32_f32_sdwa v250, v250 dst_sel:WORD_1 dst_unused:UNUSED_PAD src0_sel:DWORD
	v_cvt_i32_f32_sdwa v254, v254 dst_sel:WORD_1 dst_unused:UNUSED_PAD src0_sel:DWORD
	v_lshlrev_b32_e32 v245, 8, v245
	v_lshlrev_b32_e32 v241, 8, v241
	v_or_b32_sdwa v244, v247, v244 dst_sel:DWORD dst_unused:UNUSED_PAD src0_sel:DWORD src1_sel:BYTE_0
	v_or_b32_sdwa v240, v243, v240 dst_sel:DWORD dst_unused:UNUSED_PAD src0_sel:DWORD src1_sel:BYTE_0
	v_lshlrev_b32_e32 v243, 8, v253
	v_lshlrev_b32_e32 v247, 8, v249
	v_or_b32_sdwa v252, v255, v252 dst_sel:DWORD dst_unused:UNUSED_PAD src0_sel:DWORD src1_sel:BYTE_0
; DI float dec_key(unsigned k) { const unsigned u = (k & 0x80000000u) ? (k & 0x7fffffffu) : ~k; return __uint_as_float(u); }
; DI void cvt_linear_fp8(const float* __restrict__ src, unsigned char* __restrict__ dst, size_t n16, float scale, size_t gtid, size_t gsz) {
;   for (size_t i = gtid; i < n16; i += gsz) {
;     const float4 a = *(const float4*)(src + i * 16), b = *(const float4*)(src + i * 16 + 4), c = *(const float4*)(src + i * 16 + 8), d = *(const float4*)(src + i * 16 + 12);
;     uint4 r;
;     r.x = pk4_fp8(a.x * scale, a.y * scale, a.z * scale, a.w * scale); r.y = pk4_fp8(b.x * scale, b.y * scale, b.z * scale, b.w * scale);
;     r.z = pk4_fp8(c.x * scale, c.y * scale, c.z * scale, c.w * scale); r.w = pk4_fp8(d.x * scale, d.y * scale, d.z * scale, d.w * scale);
;     *(uint4*)(dst + i * 16) = r;
;   }
; }
; DI void phase_peer_q(const Params& p, char* smem) {
;     ...
;     if (tid < 128) {
;       constexpr CandTab CT = make_cands();
;       float s1[16], s2[16];
; #pragma unroll
;       for (int i = 0; i < 16; ++i) { s1[i] = dec_key(R[i] & ~127u); s2[i] = dec_key(xch[(tok * 2 + 1) * 16 + i] & ~127u); }
	v_or_b32_sdwa v248, v251, v248 dst_sel:DWORD dst_unused:UNUSED_PAD src0_sel:DWORD src1_sel:BYTE_0
	v_and_b32_e32 v245, 0xff00, v245
	v_and_b32_e32 v241, 0xff00, v241
	v_and_b32_e32 v243, 0xff00, v243
	v_and_b32_e32 v247, 0xff00, v247
	v_and_b32_e32 v246, 0xff0000, v246
	v_and_b32_e32 v242, 0xff0000, v242
	v_and_b32_e32 v249, 0xff0000, v254
	v_and_b32_e32 v250, 0xff0000, v250
	v_or_b32_e32 v244, v244, v245
	v_or_b32_e32 v240, v240, v241
	v_or_b32_e32 v243, v252, v243
	v_or_b32_e32 v245, v248, v247
	v_or_b32_e32 v241, v244, v246
	v_or_b32_e32 v240, v240, v242
	v_or_b32_e32 v243, v243, v249
	v_or_b32_e32 v242, v245, v250
	s_add_u32 s89, s93, 8192
	s_lshl_b32 s88, s89, 10
	s_add_u32 s86, s72, s88
	s_addc_u32 s87, s73, 0
	s_add_u32 s86, s86, 0x4c00000
	s_addc_u32 s87, s87, 0
	global_store_dwordx4 v226, v[240:243], s[86:87]
	v_mul_f32_e32 v185, 0x3c010204, v185
	s_lshl_b32 s88, s89, 2
	s_add_u32 s86, s72, s88
	s_addc_u32 s87, s73, 0
	s_add_u32 s86, s86, 0x1ec01000
	s_addc_u32 s87, s87, 0
	v_mov_b32_e32 v227, 0
	s_mov_b64 exec, s[90:91]
	global_store_dword v227, v185, s[86:87]
	s_mov_b64 exec, -1
	s_add_u32 s89, s93, 8192
	s_lshl_b32 s88, s89, 12
	s_add_u32 s86, s100, s88
	s_addc_u32 s87, s101, 0
	global_load_dwordx4 v[240:243], v225, s[86:87] nt
	global_load_dwordx4 v[244:247], v225, s[86:87] offset:16 nt
	global_load_dwordx4 v[248:251], v225, s[86:87] offset:32 nt
	global_load_dwordx4 v[252:255], v225, s[86:87] offset:48 nt
	s_waitcnt vmcnt(6)
	v_mov_b32_e32 v188, 0
	v_mov_b32_e32 v189, 0
	v_mov_b32_e32 v190, 0
	v_mov_b32_e32 v191, 0
	v_mul_f32_e32 v185, 0x41000000, v202
	v_mul_f32_e32 v186, 0x41000000, v203
	v_mul_f32_e32 v187, 0x41000000, v204
	v_mul_f32_e32 v202, 0x41000000, v205
	v_mul_f32_e32 v203, 0x41000000, v206
	v_mul_f32_e32 v204, 0x41000000, v207
	v_mul_f32_e32 v205, 0x41000000, v208
	v_mul_f32_e32 v206, 0x41000000, v209
	v_mul_f32_e32 v207, 0x41000000, v210
	v_mul_f32_e32 v208, 0x41000000, v211
	v_mul_f32_e32 v209, 0x41000000, v212
	v_mul_f32_e32 v211, 0x41000000, v214
	v_mul_f32_e32 v212, 0x41000000, v215
	v_cvt_pk_fp8_f32 v188, v185, v186
	v_cvt_pk_fp8_f32 v189, v203, v204
	v_cvt_pk_fp8_f32 v190, v207, v208
	v_cvt_pk_fp8_f32 v191, v211, v212
	v_mul_f32_e32 v210, 0x41000000, v213
	v_mul_f32_e32 v213, 0x41000000, v216
	v_mul_f32_e32 v214, 0x41000000, v217
	v_cvt_pk_fp8_f32 v188, v187, v202 op_sel:[0,0,1]
	v_cvt_pk_fp8_f32 v189, v205, v206 op_sel:[0,0,1]
	v_cvt_pk_fp8_f32 v190, v209, v210 op_sel:[0,0,1]
	v_cvt_pk_fp8_f32 v191, v213, v214 op_sel:[0,0,1]
	s_mov_b32 s89, s93
	s_lshl_b32 s88, s89, 10
	s_add_u32 s86, s72, s88
	s_addc_u32 s87, s73, 0
	s_add_u32 s86, s86, 0x6c00000
	s_addc_u32 s87, s87, 0
	global_store_dwordx4 v226, v[188:191], s[86:87]
	s_waitcnt vmcnt(1)
	v_mov_b32_e32 v196, 0
	v_mov_b32_e32 v197, 0
	v_mov_b32_e32 v198, 0
	v_mov_b32_e32 v199, 0
	v_mul_f32_e32 v185, 0x41000000, v240
	v_mul_f32_e32 v186, 0x41000000, v241
	v_mul_f32_e32 v187, 0x41000000, v242
	v_mul_f32_e32 v240, 0x41000000, v243
	v_mul_f32_e32 v241, 0x41000000, v244
	v_mul_f32_e32 v242, 0x41000000, v245
	v_mul_f32_e32 v243, 0x41000000, v246
	v_mul_f32_e32 v244, 0x41000000, v247
	v_mul_f32_e32 v245, 0x41000000, v248
	v_mul_f32_e32 v246, 0x41000000, v249
	v_mul_f32_e32 v247, 0x41000000, v250
	v_mul_f32_e32 v249, 0x41000000, v252
	v_mul_f32_e32 v250, 0x41000000, v253
	v_cvt_pk_fp8_f32 v196, v185, v186
	v_cvt_pk_fp8_f32 v197, v241, v242
	v_cvt_pk_fp8_f32 v198, v245, v246
	v_cvt_pk_fp8_f32 v199, v249, v250
	v_mul_f32_e32 v248, 0x41000000, v251
	v_mul_f32_e32 v251, 0x41000000, v254
	v_mul_f32_e32 v252, 0x41000000, v255
	v_cvt_pk_fp8_f32 v196, v187, v240 op_sel:[0,0,1]
	v_cvt_pk_fp8_f32 v197, v243, v244 op_sel:[0,0,1]
	v_cvt_pk_fp8_f32 v198, v247, v248 op_sel:[0,0,1]
	v_cvt_pk_fp8_f32 v199, v251, v252 op_sel:[0,0,1]
	s_add_u32 s89, s93, 8192
	s_lshl_b32 s88, s89, 10
	s_add_u32 s86, s72, s88
	s_addc_u32 s87, s73, 0
	s_add_u32 s86, s86, 0x6c00000
	s_addc_u32 s87, s87, 0
	global_store_dwordx4 v226, v[196:199], s[86:87]
.Lmy_cv_done:
	s_waitcnt lgkmcnt(0)
	s_barrier
	s_and_saveexec_b64 s[10:11], s[8:9]
	s_cbranch_execz .LBB0_396
	ds_read_b128 v[22:25], v124 offset:64
	ds_read_b128 v[26:29], v124 offset:80
	ds_read_b128 v[54:57], v124 offset:96
	ds_read_b128 v[18:21], v124 offset:112
	v_and_b32_e32 v30, 0xffffff80, v5
	s_waitcnt lgkmcnt(3)
	v_and_b32_e32 v31, 0xffffff80, v25
	v_and_b32_e32 v32, 0x7fffff80, v25
	v_xor_b32_e32 v31, -1, v31
	v_cmp_gt_i32_e32 vcc, 0, v25
	v_and_b32_e32 v33, 0x7fffff80, v5
	v_xor_b32_e32 v30, -1, v30
	v_cndmask_b32_e32 v34, v31, v32, vcc
	v_cmp_gt_i32_e32 vcc, 0, v5
	v_and_b32_e32 v25, 0xffffff80, v24
	v_and_b32_e32 v31, 0x7fffff80, v24
	v_cndmask_b32_e32 v36, v30, v33, vcc
	v_and_b32_e32 v30, 0xffffff80, v6
	v_xor_b32_e32 v25, -1, v25
	v_cmp_gt_i32_e32 vcc, 0, v24
	v_and_b32_e32 v32, 0x7fffff80, v6
	v_xor_b32_e32 v30, -1, v30
	v_cndmask_b32_e32 v35, v25, v31, vcc
	v_cmp_gt_i32_e32 vcc, 0, v6
	s_waitcnt lgkmcnt(2)
	v_and_b32_e32 v24, 0xffffff80, v26
	v_and_b32_e32 v25, 0xffffff80, v4
	v_cndmask_b32_e32 v30, v30, v32, vcc
	v_and_b32_e32 v31, 0x7fffff80, v26
	v_xor_b32_e32 v24, -1, v24
	v_cmp_gt_i32_e32 vcc, 0, v26
	v_and_b32_e32 v32, 0x7fffff80, v4
	v_xor_b32_e32 v25, -1, v25
	v_cndmask_b32_e32 v39, v24, v31, vcc
	v_cmp_gt_i32_e32 vcc, 0, v4
	v_and_b32_e32 v24, 0x7fffff80, v7
	v_and_b32_e32 v31, 0x7fffff80, v3
	v_cndmask_b32_e32 v40, v25, v32, vcc
	v_bitop3_b32 v25, v7, s67, v7 bitop3:0xcf
	v_cmp_gt_i32_e32 vcc, 0, v7
	v_and_b32_e32 v37, 0x7fffff80, v12
	s_waitcnt lgkmcnt(1)
; DI unsigned enc_key(float s) { const unsigned u = __float_as_uint(s); return (u & 0x80000000u) ? ~u : (u | 0x80000000u); }
; DI float dec_key(unsigned k) { const unsigned u = (k & 0x80000000u) ? (k & 0x7fffffffu) : ~k; return __uint_as_float(u); }
; DI void phase_peer_q(const Params& p, char* smem) {
;     ...
;       for (int i = 0; i < 16; ++i) { s1[i] = dec_key(R[i] & ~127u); s2[i] = dec_key(xch[(tok * 2 + 1) * 16 + i] & ~127u); }
;       unsigned B[16];
; #pragma unroll
;       for (int gi = 0; gi < 4; ++gi) {
;         unsigned X[16];
; #pragma unroll
;         for (int i = 0; i < 16; ++i) {
;           const int c = gi * 16 + i;
;           X[i] = (c < CT.n) ? ((enc_key(s1[CT.i[c]] + s2[CT.j[c]]) & ~255u) | (unsigned)(255 - (CT.i[c] * 16 + CT.j[c]))) : 0u;
;         }
;         sort16_desc(X);
	v_and_b32_e32 v66, 0x7fffff80, v55
	v_cndmask_b32_e32 v32, v25, v24, vcc
	v_and_b32_e32 v24, 0x7fffff80, v27
	v_bitop3_b32 v25, v27, s67, v27 bitop3:0xcf
	v_cmp_gt_i32_e32 vcc, 0, v27
	v_and_b32_e32 v27, 0x7fffff80, v23
	v_and_b32_e32 v67, 0x7fffff80, v54
	v_cndmask_b32_e32 v38, v25, v24, vcc
	v_and_b32_e32 v24, 0x7fffff80, v8
	v_bitop3_b32 v25, v8, s67, v8 bitop3:0xcf
	v_cmp_gt_i32_e32 vcc, 0, v8
	v_and_b32_e32 v45, 0xffffff80, v17
	v_and_b32_e32 v41, 0x7fffff80, v11
	v_cndmask_b32_e32 v26, v25, v24, vcc
	v_and_b32_e32 v24, 0x7fffff80, v28
	v_bitop3_b32 v25, v28, s67, v28 bitop3:0xcf
	v_cmp_gt_i32_e32 vcc, 0, v28
	v_and_b32_e32 v28, 0x7fffff80, v9
	v_and_b32_e32 v33, 0x7fffff80, v10
	v_cndmask_b32_e32 v43, v25, v24, vcc
	v_and_b32_e32 v24, 0xffffff80, v23
	v_and_b32_e32 v25, 0xffffff80, v9
	v_xor_b32_e32 v24, -1, v24
	v_cmp_gt_i32_e32 vcc, 0, v23
	v_xor_b32_e32 v25, -1, v25
	v_and_b32_e32 v23, 0xffffff80, v29
	v_cndmask_b32_e32 v24, v24, v27, vcc
	v_cmp_gt_i32_e32 vcc, 0, v9
	v_and_b32_e32 v27, 0x7fffff80, v29
	v_xor_b32_e32 v23, -1, v23
	v_cndmask_b32_e32 v28, v25, v28, vcc
	v_and_b32_e32 v25, 0xffffff80, v3
	v_xor_b32_e32 v25, -1, v25
	v_cmp_gt_i32_e32 vcc, 0, v3
	v_and_b32_e32 v49, 0xffffff80, v15
	v_and_b32_e32 v50, 0xffffff80, v14
	v_cndmask_b32_e32 v44, v25, v31, vcc
	v_cmp_gt_i32_e32 vcc, 0, v29
	v_and_b32_e32 v25, 0xffffff80, v12
	v_and_b32_e32 v31, 0x7fffff80, v22
	v_cndmask_b32_e32 v42, v23, v27, vcc
	v_and_b32_e32 v23, 0xffffff80, v22
	v_xor_b32_e32 v23, -1, v23
	v_cmp_gt_i32_e32 vcc, 0, v22
	v_xor_b32_e32 v53, -1, v25
	s_waitcnt lgkmcnt(0)
	v_and_b32_e32 v22, 0x7fffff80, v20
	v_cndmask_b32_e32 v25, v23, v31, vcc
	v_cmp_gt_i32_e32 vcc, 0, v12
	v_bitop3_b32 v31, v20, s67, v20 bitop3:0xcf
	v_and_b32_e32 v27, 0xffffff80, v11
	v_cndmask_b32_e32 v23, v53, v37, vcc
	v_cmp_gt_i32_e32 vcc, 0, v20
	v_and_b32_e32 v20, 0x7fffff80, v13
	v_and_b32_e32 v37, 0x7fffff80, v21
	v_cndmask_b32_e32 v59, v31, v22, vcc
	v_bitop3_b32 v22, v13, s67, v13 bitop3:0xcf
	v_cmp_gt_i32_e32 vcc, 0, v13
	v_and_b32_e32 v31, 0xffffff80, v2
	v_and_b32_e32 v53, 0x7fffff80, v2
	v_cndmask_b32_e32 v22, v22, v20, vcc
	v_and_b32_e32 v20, 0xffffff80, v21
	v_xor_b32_e32 v20, -1, v20
	v_cmp_gt_i32_e32 vcc, 0, v21
	v_xor_b32_e32 v31, -1, v31
	v_and_b32_e32 v29, 0xffffff80, v10
	v_cndmask_b32_e32 v58, v20, v37, vcc
	v_cmp_gt_i32_e32 vcc, 0, v2
	v_and_b32_e32 v52, 0x7fffff80, v15
	v_and_b32_e32 v51, 0x7fffff80, v14
	v_cndmask_b32_e32 v20, v31, v53, vcc
	v_pk_add_f32 v[60:61], v[20:21], v[24:25] op_sel_hi:[0,1]
	v_not_b32_e32 v21, v61
	v_or_b32_e32 v31, 0x80000000, v61
	v_cmp_gt_i32_e32 vcc, 0, v61
	v_or_b32_e32 v37, 0x80000000, v60
	v_and_b32_e32 v46, 0xffffff80, v16
	v_cndmask_b32_e32 v21, v31, v21, vcc
	v_or_b32_e32 v21, 0xff, v21
	v_not_b32_e32 v31, v60
	v_cmp_gt_i32_e32 vcc, 0, v60
	v_pk_add_f32 v[60:61], v[20:21], v[34:35] op_sel_hi:[0,1]
	v_or_b32_e32 v53, 0x80000000, v61
	v_cndmask_b32_e32 v31, v37, v31, vcc
	v_not_b32_e32 v37, v61
	v_cmp_gt_i32_e32 vcc, 0, v61
	v_or_b32_e32 v61, 0x80000000, v60
	v_and_b32_e32 v31, 0xffffff00, v31
	v_cndmask_b32_e32 v37, v53, v37, vcc
	v_not_b32_e32 v53, v60
	v_cmp_gt_i32_e32 vcc, 0, v60
	v_and_b32_e32 v37, 0xffffff00, v37
	v_or_b32_e32 v31, 0xfe, v31
	v_cndmask_b32_e32 v53, v61, v53, vcc
	v_pk_add_f32 v[60:61], v[20:21], v[38:39] op_sel_hi:[0,1]
	v_not_b32_e32 v62, v61
	v_or_b32_e32 v63, 0x80000000, v61
	v_cmp_gt_i32_e32 vcc, 0, v61
	v_and_b32_e32 v53, 0xffffff00, v53
	v_or_b32_e32 v37, 0xfd, v37
	v_cndmask_b32_e32 v61, v63, v62, vcc
	v_and_b32_e32 v61, 0xffffff00, v61
	v_or_b32_e32 v62, 0xfb, v61
	v_not_b32_e32 v61, v60
	v_or_b32_e32 v63, 0x80000000, v60
	v_cmp_gt_i32_e32 vcc, 0, v60
	v_or_b32_e32 v53, 0xfc, v53
	v_and_b32_e32 v48, 0x7fffff80, v17
	v_cndmask_b32_e32 v60, v63, v61, vcc
	v_and_b32_e32 v60, 0xffffff00, v60
	v_or_b32_e32 v63, 0xfa, v60
	v_pk_add_f32 v[60:61], v[20:21], v[42:43] op_sel_hi:[0,1]
	v_not_b32_e32 v64, v61
	v_or_b32_e32 v65, 0x80000000, v61
	v_cmp_gt_i32_e32 vcc, 0, v61
	v_and_b32_e32 v47, 0x7fffff80, v16
	s_nop 0
	v_cndmask_b32_e32 v61, v65, v64, vcc
	v_not_b32_e32 v64, v60
	v_or_b32_e32 v65, 0x80000000, v60
	v_cmp_gt_i32_e32 vcc, 0, v60
	v_and_b32_e32 v61, 0xffffff00, v61
	v_or_b32_e32 v61, 0xf9, v61
	v_cndmask_b32_e32 v60, v65, v64, vcc
	v_and_b32_e32 v64, 0xffffff80, v55
	v_and_b32_e32 v65, 0xffffff80, v54
	v_xor_b32_e32 v64, -1, v64
	v_cmp_gt_i32_e32 vcc, 0, v55
	v_xor_b32_e32 v65, -1, v65
	v_and_b32_e32 v60, 0xffffff00, v60
	v_cndmask_b32_e32 v55, v64, v66, vcc
	v_cmp_gt_i32_e32 vcc, 0, v54
	v_and_b32_e32 v66, 0x7fffff80, v57
	v_or_b32_e32 v60, 0xf8, v60
	v_cndmask_b32_e32 v54, v65, v67, vcc
	v_pk_add_f32 v[54:55], v[20:21], v[54:55] op_sel_hi:[0,1]
	v_not_b32_e32 v64, v54
	v_or_b32_e32 v65, 0x80000000, v54
	v_cmp_gt_i32_e32 vcc, 0, v54
	v_and_b32_e32 v67, 0x7fffff80, v56
	s_nop 0
	v_cndmask_b32_e32 v54, v65, v64, vcc
	v_and_b32_e32 v54, 0xffffff00, v54
	v_or_b32_e32 v64, 0xf7, v54
	v_not_b32_e32 v54, v55
	v_or_b32_e32 v65, 0x80000000, v55
	v_cmp_gt_i32_e32 vcc, 0, v55
	v_and_b32_e32 v55, 0xffffff80, v56
	v_xor_b32_e32 v68, -1, v55
	v_cndmask_b32_e32 v54, v65, v54, vcc
	v_and_b32_e32 v54, 0xffffff00, v54
	v_or_b32_e32 v65, 0xf6, v54
	v_and_b32_e32 v54, 0xffffff80, v57
	v_xor_b32_e32 v54, -1, v54
	v_cmp_gt_i32_e32 vcc, 0, v57
	s_nop 1
	v_cndmask_b32_e32 v55, v54, v66, vcc
	v_cmp_gt_i32_e32 vcc, 0, v56
	v_and_b32_e32 v66, 0x7fffff80, v19
	s_nop 0
	v_cndmask_b32_e32 v54, v68, v67, vcc
	v_pk_add_f32 v[54:55], v[20:21], v[54:55] op_sel_hi:[0,1]
	v_not_b32_e32 v56, v54
	v_or_b32_e32 v57, 0x80000000, v54
	v_cmp_gt_i32_e32 vcc, 0, v54
	v_and_b32_e32 v67, 0x7fffff80, v18
	s_nop 0
	v_cndmask_b32_e32 v54, v57, v56, vcc
; DI unsigned enc_key(float s) { const unsigned u = __float_as_uint(s); return (u & 0x80000000u) ? ~u : (u | 0x80000000u); }
; DI void sort16_desc(unsigned (&v)[16]) {
;   constexpr int KS[10] = {2, 4, 4, 8, 8, 8, 16, 16, 16, 16};
;   constexpr int JS[10] = {1, 2, 1, 4, 2, 1, 8, 4, 2, 1};
; #pragma unroll
;   for (int s = 0; s < 10; ++s) {
; #pragma unroll
;     for (int i = 0; i < 16; ++i) {
;       const int l = i ^ JS[s];
;       if (l > i) {
;         if ((i & KS[s]) == 0) cswap(v[i], v[l]); else cswap(v[l], v[i]);
;       }
;     }
;   }
; DI void phase_peer_q(const Params& p, char* smem) {
;     ...
;       for (int gi = 0; gi < 4; ++gi) {
;         unsigned X[16];
; #pragma unroll
;         for (int i = 0; i < 16; ++i) {
;           const int c = gi * 16 + i;
;           X[i] = (c < CT.n) ? ((enc_key(s1[CT.i[c]] + s2[CT.j[c]]) & ~255u) | (unsigned)(255 - (CT.i[c] * 16 + CT.j[c]))) : 0u;
;         }
;         sort16_desc(X);
	v_not_b32_e32 v56, v55
	v_or_b32_e32 v57, 0x80000000, v55
	v_cmp_gt_i32_e32 vcc, 0, v55
	v_and_b32_e32 v54, 0xffffff00, v54
	v_or_b32_e32 v54, 0xf5, v54
	v_cndmask_b32_e32 v55, v57, v56, vcc
	v_and_b32_e32 v56, 0xffffff80, v19
	v_and_b32_e32 v57, 0xffffff80, v18
	v_xor_b32_e32 v56, -1, v56
	v_cmp_gt_i32_e32 vcc, 0, v19
	v_xor_b32_e32 v57, -1, v57
	v_and_b32_e32 v55, 0xffffff00, v55
	v_cndmask_b32_e32 v19, v56, v66, vcc
	v_cmp_gt_i32_e32 vcc, 0, v18
	v_or_b32_e32 v55, 0xf4, v55
	s_nop 0
	v_cndmask_b32_e32 v18, v57, v67, vcc
	v_pk_add_f32 v[18:19], v[20:21], v[18:19] op_sel_hi:[0,1]
	v_not_b32_e32 v56, v18
	v_or_b32_e32 v57, 0x80000000, v18
	v_cmp_gt_i32_e32 vcc, 0, v18
	s_nop 1
	v_cndmask_b32_e32 v18, v57, v56, vcc
	v_and_b32_e32 v18, 0xffffff00, v18
	v_or_b32_e32 v56, 0xf3, v18
	v_not_b32_e32 v18, v19
	v_or_b32_e32 v57, 0x80000000, v19
	v_cmp_gt_i32_e32 vcc, 0, v19
	s_nop 1
	v_cndmask_b32_e32 v18, v57, v18, vcc
	v_and_b32_e32 v18, 0xffffff00, v18
	v_or_b32_e32 v57, 0xf2, v18
	v_pk_add_f32 v[18:19], v[20:21], v[58:59] op_sel_hi:[0,1]
	v_not_b32_e32 v20, v19
	v_or_b32_e32 v58, 0x80000000, v19
	v_cmp_gt_i32_e32 vcc, 0, v19
	v_max_u32_e32 v59, v60, v61
	v_min_u32_e32 v60, v60, v61
	v_cndmask_b32_e32 v19, v58, v20, vcc
	v_not_b32_e32 v20, v18
	v_or_b32_e32 v58, 0x80000000, v18
	v_cmp_gt_i32_e32 vcc, 0, v18
	v_and_b32_e32 v19, 0xffffff00, v19
	v_or_b32_e32 v19, 0xf1, v19
	v_cndmask_b32_e32 v18, v58, v20, vcc
	v_and_b32_e32 v18, 0xffffff00, v18
	v_or_b32_e32 v18, 0xf0, v18
	v_max_u32_e32 v20, v21, v31
	v_min_u32_e32 v21, v21, v31
	v_max_u32_e32 v31, v53, v37
	v_min_u32_e32 v37, v53, v37
	v_max_u32_e32 v53, v62, v63
	v_min_u32_e32 v58, v62, v63
	v_max_u32_e32 v61, v64, v65
	v_min_u32_e32 v62, v64, v65
	v_max_u32_e32 v63, v55, v54
	v_min_u32_e32 v54, v55, v54
	v_max_u32_e32 v55, v56, v57
	v_min_u32_e32 v56, v56, v57
	v_max_u32_e32 v57, v18, v19
	v_min_u32_e32 v18, v18, v19
	v_max_u32_e32 v19, v20, v37
	v_min_u32_e32 v20, v20, v37
	v_max_u32_e32 v37, v21, v31
	v_min_u32_e32 v21, v21, v31
	v_max_u32_e32 v31, v60, v53
	v_min_u32_e32 v53, v60, v53
	v_max_u32_e32 v60, v59, v58
	v_min_u32_e32 v58, v59, v58
	v_max_u32_e32 v59, v61, v54
	v_min_u32_e32 v54, v61, v54
	v_max_u32_e32 v61, v62, v63
	v_min_u32_e32 v62, v62, v63
	v_max_u32_e32 v63, v18, v55
	v_min_u32_e32 v18, v18, v55
	v_max_u32_e32 v55, v57, v56
	v_min_u32_e32 v56, v57, v56
	v_max_u32_e32 v57, v19, v37
	v_min_u32_e32 v19, v19, v37
	v_max_u32_e32 v37, v20, v21
	v_min_u32_e32 v20, v20, v21
	v_max_u32_e32 v21, v58, v53
	v_min_u32_e32 v53, v58, v53
	v_max_u32_e32 v58, v60, v31
	v_min_u32_e32 v31, v60, v31
	v_max_u32_e32 v60, v59, v61
	v_min_u32_e32 v59, v59, v61
	v_max_u32_e32 v61, v54, v62
	v_min_u32_e32 v54, v54, v62
	v_max_u32_e32 v62, v56, v18
	v_min_u32_e32 v18, v56, v18
	v_max_u32_e32 v56, v55, v63
	v_min_u32_e32 v55, v55, v63
	v_max_u32_e32 v63, v57, v53
	v_min_u32_e32 v53, v57, v53
	v_max_u32_e32 v57, v19, v21
	v_min_u32_e32 v19, v19, v21
	v_max_u32_e32 v21, v37, v31
	v_min_u32_e32 v31, v37, v31
	v_max_u32_e32 v37, v20, v58
	v_min_u32_e32 v20, v20, v58
	v_max_u32_e32 v58, v18, v60
	v_min_u32_e32 v18, v18, v60
	v_max_u32_e32 v60, v62, v59
	v_min_u32_e32 v59, v62, v59
	v_max_u32_e32 v62, v55, v61
	v_min_u32_e32 v55, v55, v61
	v_max_u32_e32 v61, v56, v54
	v_min_u32_e32 v54, v56, v54
	v_max_u32_e32 v56, v63, v21
	v_min_u32_e32 v21, v63, v21
	v_max_u32_e32 v63, v57, v37
	v_min_u32_e32 v37, v57, v37
	v_max_u32_e32 v57, v53, v31
	v_min_u32_e32 v31, v53, v31
	v_max_u32_e32 v53, v19, v20
	v_min_u32_e32 v19, v19, v20
	v_max_u32_e32 v20, v55, v18
	v_min_u32_e32 v18, v55, v18
	v_max_u32_e32 v55, v54, v59
	v_min_u32_e32 v54, v54, v59
	v_max_u32_e32 v59, v62, v58
	v_min_u32_e32 v58, v62, v58
	v_max_u32_e32 v62, v61, v60
	v_min_u32_e32 v60, v61, v60
	v_max_u32_e32 v61, v56, v63
	v_min_u32_e32 v56, v56, v63
	v_max_u32_e32 v63, v21, v37
	v_min_u32_e32 v21, v21, v37
	v_max_u32_e32 v37, v57, v53
	v_min_u32_e32 v53, v57, v53
	v_max_u32_e32 v57, v31, v19
	v_min_u32_e32 v19, v31, v19
	v_max_u32_e32 v31, v54, v18
	v_min_u32_e32 v18, v54, v18
	v_max_u32_e32 v54, v55, v20
	v_min_u32_e32 v20, v55, v20
	v_max_u32_e32 v55, v60, v58
	v_min_u32_e32 v58, v60, v58
	v_max_u32_e32 v60, v62, v59
	v_min_u32_e32 v59, v62, v59
	v_max_u32_e32 v62, v61, v18
	v_min_u32_e32 v18, v61, v18
	v_max_u32_e32 v61, v56, v31
	v_min_u32_e32 v31, v56, v31
	v_max_u32_e32 v56, v63, v20
	v_min_u32_e32 v20, v63, v20
	v_max_u32_e32 v63, v21, v54
	v_min_u32_e32 v21, v21, v54
	v_max_u32_e32 v54, v37, v58
	v_min_u32_e32 v37, v37, v58
	v_max_u32_e32 v58, v53, v55
	v_min_u32_e32 v53, v53, v55
	v_max_u32_e32 v55, v57, v59
	v_min_u32_e32 v57, v57, v59
	v_max_u32_e32 v59, v19, v60
	v_min_u32_e32 v19, v19, v60
	v_max_u32_e32 v60, v62, v54
	v_min_u32_e32 v54, v62, v54
	v_max_u32_e32 v62, v61, v58
	v_min_u32_e32 v58, v61, v58
	v_max_u32_e32 v61, v56, v55
	v_min_u32_e32 v55, v56, v55
	v_max_u32_e32 v56, v63, v59
	v_min_u32_e32 v59, v63, v59
	v_max_u32_e32 v63, v18, v37
	v_min_u32_e32 v18, v18, v37
	v_max_u32_e32 v37, v31, v53
	v_min_u32_e32 v31, v31, v53
	v_max_u32_e32 v53, v20, v57
	v_min_u32_e32 v20, v20, v57
	v_max_u32_e32 v57, v21, v19
	v_min_u32_e32 v19, v21, v19
	v_max_u32_e32 v65, v18, v20
	v_min_u32_e32 v66, v18, v20
	v_max_u32_e32 v67, v31, v19
	v_min_u32_e32 v31, v31, v19
	v_pk_add_f32 v[18:19], v[44:45], v[24:25] op_sel_hi:[0,1]
	v_not_b32_e32 v20, v19
	v_or_b32_e32 v21, 0x80000000, v19
	v_cmp_gt_i32_e32 vcc, 0, v19
	v_max_u32_e32 v64, v60, v61
	v_min_u32_e32 v60, v60, v61
	v_cndmask_b32_e32 v19, v21, v20, vcc
	v_and_b32_e32 v19, 0xffffff00, v19
	v_or_b32_e32 v20, 0xef, v19
	v_not_b32_e32 v19, v18
	v_or_b32_e32 v21, 0x80000000, v18
; DI unsigned enc_key(float s) { const unsigned u = __float_as_uint(s); return (u & 0x80000000u) ? ~u : (u | 0x80000000u); }
; DI void sort16_desc(unsigned (&v)[16]) {
;   constexpr int KS[10] = {2, 4, 4, 8, 8, 8, 16, 16, 16, 16};
;   constexpr int JS[10] = {1, 2, 1, 4, 2, 1, 8, 4, 2, 1};
; #pragma unroll
;   for (int s = 0; s < 10; ++s) {
; #pragma unroll
;     for (int i = 0; i < 16; ++i) {
;       const int l = i ^ JS[s];
;       if (l > i) {
;         if ((i & KS[s]) == 0) cswap(v[i], v[l]); else cswap(v[l], v[i]);
;       }
;     }
;   }
; DI void phase_peer_q(const Params& p, char* smem) {
;     ...
;       for (int gi = 0; gi < 4; ++gi) {
;         unsigned X[16];
; #pragma unroll
;         for (int i = 0; i < 16; ++i) {
;           const int c = gi * 16 + i;
;           X[i] = (c < CT.n) ? ((enc_key(s1[CT.i[c]] + s2[CT.j[c]]) & ~255u) | (unsigned)(255 - (CT.i[c] * 16 + CT.j[c]))) : 0u;
;         }
;         sort16_desc(X);
;         if (gi == 0) {
; #pragma unroll
;           for (int i = 0; i < 16; ++i) B[i] = X[i];
;         } else merge16_desc(B, X);
	v_cmp_gt_i32_e32 vcc, 0, v18
	v_max_u32_e32 v61, v62, v56
	v_min_u32_e32 v56, v62, v56
	v_cndmask_b32_e32 v18, v21, v19, vcc
	v_and_b32_e32 v18, 0xffffff00, v18
	v_or_b32_e32 v21, 0xee, v18
	v_pk_add_f32 v[18:19], v[44:45], v[34:35] op_sel_hi:[0,1]
	v_max_u32_e32 v62, v54, v55
	v_min_u32_e32 v54, v54, v55
	v_max_u32_e32 v55, v58, v59
	v_min_u32_e32 v58, v58, v59
	v_max_u32_e32 v59, v63, v53
	v_min_u32_e32 v53, v63, v53
	v_max_u32_e32 v63, v37, v57
	v_min_u32_e32 v57, v37, v57
	v_not_b32_e32 v37, v19
	v_or_b32_e32 v76, 0x80000000, v19
	v_cmp_gt_i32_e32 vcc, 0, v19
	v_min_u32_e32 v68, v64, v61
	v_min_u32_e32 v69, v60, v56
	v_cndmask_b32_e32 v19, v76, v37, vcc
	v_and_b32_e32 v19, 0xffffff00, v19
	v_or_b32_e32 v76, 0xed, v19
	v_not_b32_e32 v19, v18
	v_or_b32_e32 v37, 0x80000000, v18
	v_cmp_gt_i32_e32 vcc, 0, v18
	v_min_u32_e32 v70, v62, v55
	v_min_u32_e32 v71, v54, v58
	v_cndmask_b32_e32 v18, v37, v19, vcc
	v_and_b32_e32 v18, 0xffffff00, v18
	v_or_b32_e32 v77, 0xec, v18
	v_pk_add_f32 v[18:19], v[44:45], v[38:39] op_sel_hi:[0,1]
	v_not_b32_e32 v37, v19
	v_or_b32_e32 v38, 0x80000000, v19
	v_cmp_gt_i32_e32 vcc, 0, v19
	v_min_u32_e32 v72, v59, v63
	v_min_u32_e32 v73, v53, v57
	v_cndmask_b32_e32 v19, v38, v37, vcc
	v_and_b32_e32 v19, 0xffffff00, v19
	v_or_b32_e32 v78, 0xeb, v19
	v_not_b32_e32 v19, v18
	v_or_b32_e32 v37, 0x80000000, v18
	v_cmp_gt_i32_e32 vcc, 0, v18
	v_min_u32_e32 v74, v65, v67
	v_min_u32_e32 v75, v66, v31
	v_cndmask_b32_e32 v18, v37, v19, vcc
	v_and_b32_e32 v18, 0xffffff00, v18
	v_or_b32_e32 v79, 0xea, v18
	v_pk_add_f32 v[18:19], v[44:45], v[42:43] op_sel_hi:[0,1]
	v_not_b32_e32 v37, v19
	v_or_b32_e32 v38, 0x80000000, v19
	v_cmp_gt_i32_e32 vcc, 0, v19
	v_min_u32_e32 v95, v78, v79
	s_nop 0
	v_cndmask_b32_e32 v19, v38, v37, vcc
	v_and_b32_e32 v19, 0xffffff00, v19
	v_or_b32_e32 v42, 0xe9, v19
	v_not_b32_e32 v19, v18
	v_or_b32_e32 v37, 0x80000000, v18
	v_cmp_gt_i32_e32 vcc, 0, v18
	s_nop 1
	v_cndmask_b32_e32 v18, v37, v19, vcc
	v_and_b32_e32 v18, 0xffffff00, v18
	v_or_b32_e32 v43, 0xe8, v18
	v_pk_add_f32 v[18:19], v[40:41], v[24:25] op_sel_hi:[0,1]
	v_not_b32_e32 v37, v19
	v_or_b32_e32 v38, 0x80000000, v19
	v_cmp_gt_i32_e32 vcc, 0, v19
	s_nop 1
	v_cndmask_b32_e32 v19, v38, v37, vcc
	v_and_b32_e32 v19, 0xffffff00, v19
	v_or_b32_e32 v44, 0xdf, v19
	v_not_b32_e32 v19, v18
	v_or_b32_e32 v37, 0x80000000, v18
	v_cmp_gt_i32_e32 vcc, 0, v18
	s_nop 1
	v_cndmask_b32_e32 v18, v37, v19, vcc
	v_and_b32_e32 v18, 0xffffff00, v18
	v_or_b32_e32 v80, 0xde, v18
	v_pk_add_f32 v[18:19], v[40:41], v[34:35] op_sel_hi:[0,1]
	v_not_b32_e32 v37, v19
	v_or_b32_e32 v38, 0x80000000, v19
	v_cmp_gt_i32_e32 vcc, 0, v19
	v_max_u32_e32 v104, v44, v80
	v_min_u32_e32 v44, v44, v80
	v_cndmask_b32_e32 v19, v38, v37, vcc
	v_and_b32_e32 v19, 0xffffff00, v19
	v_or_b32_e32 v81, 0xdd, v19
	v_not_b32_e32 v19, v18
	v_or_b32_e32 v37, 0x80000000, v18
	v_cmp_gt_i32_e32 vcc, 0, v18
	v_mov_b32_e32 v38, v25
	s_nop 0
	v_cndmask_b32_e32 v18, v37, v19, vcc
	v_and_b32_e32 v18, 0xffffff00, v18
	v_mov_b32_e32 v37, v40
	v_or_b32_e32 v94, 0xdc, v18
	v_pk_add_f32 v[18:19], v[36:37], v[38:39]
	v_min_u32_e32 v105, v94, v81
	v_not_b32_e32 v37, v19
	v_or_b32_e32 v38, 0x80000000, v19
	v_cmp_gt_i32_e32 vcc, 0, v19
	v_max_u32_e32 v80, v94, v81
	v_min_u32_e32 v157, v104, v105
	v_cndmask_b32_e32 v19, v38, v37, vcc
	v_and_b32_e32 v19, 0xffffff00, v19
	v_or_b32_e32 v37, 0xdb, v19
	v_not_b32_e32 v19, v18
	v_or_b32_e32 v38, 0x80000000, v18
	v_cmp_gt_i32_e32 vcc, 0, v18
	v_min_u32_e32 v81, v44, v80
	v_max_u32_e32 v44, v44, v80
	v_cndmask_b32_e32 v18, v38, v19, vcc
	v_and_b32_e32 v18, 0xffffff00, v18
	v_or_b32_e32 v38, 0xcf, v18
	v_max_u32_e32 v18, v20, v21
	v_min_u32_e32 v19, v77, v76
	v_min_u32_e32 v20, v20, v21
	v_max_u32_e32 v21, v77, v76
	v_max_u32_e32 v39, v18, v19
	v_max_u32_e32 v77, v43, v42
	v_min_u32_e32 v42, v43, v42
	v_max_u32_e32 v43, v78, v79
	v_min_u32_e32 v18, v18, v19
	v_min_u32_e32 v19, v20, v21
	v_max_u32_e32 v40, v20, v21
	v_min_u32_e32 v96, v77, v95
	v_min_u32_e32 v78, v42, v43
	v_max_u32_e32 v98, v18, v19
	v_max_u32_e32 v20, v77, v95
	v_max_u32_e32 v21, v42, v43
	v_min_u32_e32 v95, v18, v19
	v_mov_b32_e32 v18, v35
	v_mov_b32_e32 v19, v24
	v_max_u32_e32 v76, v39, v40
	v_min_u32_e32 v79, v96, v78
	v_min_u32_e32 v42, v20, v21
	v_min_u32_e32 v39, v39, v40
	v_max_u32_e32 v40, v96, v78
	v_max_u32_e32 v96, v20, v21
	v_pk_add_f32 v[20:21], v[36:37], v[18:19] op_sel_hi:[0,1]
	v_not_b32_e32 v35, v21
	v_or_b32_e32 v102, 0x80000000, v21
	v_cmp_gt_i32_e32 vcc, 0, v21
	v_min_u32_e32 v94, v157, v81
	v_max_u32_e32 v81, v157, v81
	v_cndmask_b32_e32 v21, v102, v35, vcc
	v_not_b32_e32 v35, v20
	v_or_b32_e32 v102, 0x80000000, v20
	v_cmp_gt_i32_e32 vcc, 0, v20
	v_and_b32_e32 v21, 0xffffff00, v21
	v_or_b32_e32 v21, 0xce, v21
	v_cndmask_b32_e32 v20, v102, v35, vcc
	v_and_b32_e32 v20, 0xffffff00, v20
	v_or_b32_e32 v20, 0xcd, v20
	v_max_u32_e32 v35, v20, v21
	v_min_u32_e32 v102, v37, v38
	v_min_u32_e32 v20, v20, v21
	v_max_u32_e32 v21, v37, v38
	v_max_u32_e32 v103, v35, v102
	v_max_u32_e32 v37, v20, v21
	v_min_u32_e32 v35, v35, v102
	v_min_u32_e32 v20, v20, v21
	v_max_u32_e32 v102, v104, v105
	v_max_u32_e32 v38, v103, v37
	v_max_u32_e32 v21, v35, v20
	v_min_u32_e32 v80, v102, v44
	v_min_u32_e32 v37, v103, v37
	v_min_u32_e32 v20, v35, v20
	v_max_u32_e32 v35, v102, v44
	v_max_u32_e32 v97, v76, v79
	v_max_u32_e32 v43, v98, v42
	v_max_u32_e32 v78, v39, v40
	v_max_u32_e32 v99, v95, v96
	v_min_u32_e32 v158, v38, v94
	v_min_u32_e32 v104, v21, v80
	v_min_u32_e32 v103, v37, v81
	v_min_u32_e32 v44, v20, v35
	v_min_u32_e32 v76, v76, v79
	v_min_u32_e32 v42, v98, v42
	v_min_u32_e32 v39, v39, v40
	v_min_u32_e32 v40, v95, v96
; DI unsigned enc_key(float s) { const unsigned u = __float_as_uint(s); return (u & 0x80000000u) ? ~u : (u | 0x80000000u); }
; DI void merge16_desc(unsigned (&R)[16], const unsigned (&X)[16]) {
; #pragma unroll
;   for (int i = 0; i < 16; ++i) R[i] = R[i] > X[15 - i] ? R[i] : X[15 - i];
;   constexpr int JS[4] = {8, 4, 2, 1};
; #pragma unroll
;   for (int s = 0; s < 4; ++s) {
; #pragma unroll
;     for (int i = 0; i < 16; ++i) {
;       const int l = i ^ JS[s];
;       if (l > i) cswap(R[i], R[l]);
;     }
;   }
; }
; DI void phase_peer_q(const Params& p, char* smem) {
;     ...
;       for (int gi = 0; gi < 4; ++gi) {
;         unsigned X[16];
; #pragma unroll
;         for (int i = 0; i < 16; ++i) {
;           const int c = gi * 16 + i;
;           X[i] = (c < CT.n) ? ((enc_key(s1[CT.i[c]] + s2[CT.j[c]]) & ~255u) | (unsigned)(255 - (CT.i[c] * 16 + CT.j[c]))) : 0u;
;         }
;         sort16_desc(X);
;         if (gi == 0) {
; #pragma unroll
;           for (int i = 0; i < 16; ++i) B[i] = X[i];
;         } else merge16_desc(B, X);
	v_max_u32_e32 v38, v38, v94
	v_max_u32_e32 v21, v21, v80
	v_max_u32_e32 v37, v37, v81
	v_max_u32_e32 v20, v20, v35
	v_max_u32_e32 v77, v97, v43
	v_max_u32_e32 v100, v78, v99
	v_min_u32_e32 v105, v158, v104
	v_min_u32_e32 v102, v103, v44
	v_max_u32_e32 v79, v76, v42
	v_max_u32_e32 v95, v39, v40
	v_min_u32_e32 v80, v38, v21
	v_min_u32_e32 v35, v37, v20
	v_min_u32_e32 v43, v97, v43
	v_min_u32_e32 v78, v78, v99
	v_max_u32_e32 v99, v158, v104
	v_max_u32_e32 v44, v103, v44
	v_min_u32_e32 v42, v76, v42
	v_min_u32_e32 v39, v39, v40
	v_max_u32_e32 v21, v38, v21
	v_max_u32_e32 v20, v37, v20
	v_max_u32_e32 v101, v77, v100
	v_min_u32_e32 v157, v105, v102
	v_max_u32_e32 v96, v79, v95
	v_min_u32_e32 v81, v80, v35
	v_max_u32_e32 v97, v43, v78
	v_min_u32_e32 v103, v99, v44
	v_max_u32_e32 v40, v42, v39
	v_min_u32_e32 v37, v21, v20
	v_min_u32_e32 v159, v101, v157
	v_min_u32_e32 v94, v96, v81
	v_min_u32_e32 v104, v97, v103
	v_min_u32_e32 v38, v40, v37
	v_min_u32_e32 v98, v159, v94
	v_min_u32_e32 v76, v104, v38
	v_min_u32_e32 v77, v77, v100
	v_max_u32_e32 v100, v105, v102
	v_min_u32_e32 v79, v79, v95
	v_max_u32_e32 v35, v80, v35
	v_min_u32_e32 v43, v43, v78
	v_max_u32_e32 v44, v99, v44
	v_min_u32_e32 v39, v42, v39
	v_max_u32_e32 v20, v21, v20
	v_max_u32_e32 v94, v159, v94
	v_max_u32_e32 v38, v104, v38
	v_min_u32_e32 v158, v98, v76
	v_min_u32_e32 v102, v77, v100
	v_min_u32_e32 v80, v79, v35
	v_min_u32_e32 v78, v43, v44
	v_min_u32_e32 v21, v39, v20
	v_max_u32_e32 v76, v98, v76
	v_min_u32_e32 v98, v94, v38
	v_max_u32_e32 v38, v94, v38
	v_max_u32_e32 v94, v101, v157
	v_max_u32_e32 v81, v96, v81
	v_max_u32_e32 v97, v97, v103
	v_max_u32_e32 v37, v40, v37
	v_max_u32_e32 v77, v77, v100
	v_max_u32_e32 v35, v79, v35
	v_max_u32_e32 v43, v43, v44
	v_max_u32_e32 v20, v39, v20
	v_min_u32_e32 v95, v102, v80
	v_min_u32_e32 v42, v78, v21
	v_max_u32_e32 v80, v102, v80
	v_max_u32_e32 v21, v78, v21
	v_min_u32_e32 v96, v94, v81
	v_min_u32_e32 v40, v97, v37
	v_min_u32_e32 v79, v77, v35
	v_min_u32_e32 v39, v43, v20
	v_max_u32_e32 v81, v94, v81
	v_max_u32_e32 v37, v97, v37
	v_max_u32_e32 v35, v77, v35
	v_max_u32_e32 v20, v43, v20
	v_min_u32_e32 v99, v95, v42
	v_max_u32_e32 v42, v95, v42
	v_min_u32_e32 v78, v80, v21
	v_max_u32_e32 v21, v80, v21
	v_min_u32_e32 v101, v96, v40
	v_min_u32_e32 v44, v79, v39
	v_max_u32_e32 v40, v96, v40
	v_max_u32_e32 v39, v79, v39
	v_min_u32_e32 v94, v81, v37
	v_min_u32_e32 v43, v35, v20
	v_max_u32_e32 v37, v81, v37
	v_max_u32_e32 v20, v35, v20
	v_min_u32_e32 v105, v158, v99
	v_min_u32_e32 v95, v76, v42
	v_min_u32_e32 v102, v98, v78
	v_min_u32_e32 v80, v38, v21
	v_min_u32_e32 v100, v101, v44
	v_min_u32_e32 v79, v40, v39
	v_min_u32_e32 v77, v94, v43
	v_min_u32_e32 v35, v37, v20
	v_max3_u32 v61, v64, v61, v105
	v_max3_u32 v64, v68, v158, v99
	v_max3_u32 v56, v60, v56, v95
	v_max3_u32 v42, v69, v76, v42
	v_max3_u32 v55, v62, v55, v102
	v_max3_u32 v60, v70, v98, v78
	v_max3_u32 v54, v54, v58, v80
	v_max3_u32 v21, v71, v38, v21
	v_max3_u32 v38, v59, v63, v100
	v_max3_u32 v44, v72, v101, v44
	v_max3_u32 v53, v53, v57, v79
	v_max3_u32 v39, v73, v40, v39
	v_max3_u32 v40, v65, v67, v77
	v_max3_u32 v43, v74, v94, v43
	v_max3_u32 v31, v66, v31, v35
	v_max3_u32 v20, v75, v37, v20
	v_max_u32_e32 v35, v61, v38
	v_min_u32_e32 v37, v61, v38
	v_max_u32_e32 v38, v64, v44
	v_min_u32_e32 v44, v64, v44
	v_max_u32_e32 v57, v56, v53
	v_min_u32_e32 v53, v56, v53
	v_max_u32_e32 v56, v42, v39
	v_min_u32_e32 v39, v42, v39
	v_max_u32_e32 v42, v55, v40
	v_min_u32_e32 v40, v55, v40
	v_max_u32_e32 v55, v60, v43
	v_min_u32_e32 v43, v60, v43
	v_max_u32_e32 v58, v54, v31
	v_min_u32_e32 v31, v54, v31
	v_max_u32_e32 v54, v21, v20
	v_min_u32_e32 v20, v21, v20
	v_max_u32_e32 v21, v35, v42
	v_min_u32_e32 v35, v35, v42
	v_max_u32_e32 v42, v38, v55
	v_min_u32_e32 v38, v38, v55
	v_max_u32_e32 v55, v57, v58
	v_min_u32_e32 v57, v57, v58
	v_max_u32_e32 v58, v56, v54
	v_min_u32_e32 v54, v56, v54
	v_max_u32_e32 v56, v37, v40
	v_min_u32_e32 v37, v37, v40
	v_max_u32_e32 v40, v44, v43
	v_min_u32_e32 v43, v44, v43
	v_max_u32_e32 v44, v53, v31
	v_min_u32_e32 v31, v53, v31
	v_max_u32_e32 v53, v39, v20
	v_min_u32_e32 v20, v39, v20
	v_max_u32_e32 v39, v21, v55
	v_min_u32_e32 v55, v21, v55
	v_max_u32_e32 v59, v42, v58
	v_min_u32_e32 v42, v42, v58
	v_max_u32_e32 v58, v35, v57
	v_min_u32_e32 v35, v35, v57
	v_max_u32_e32 v57, v38, v54
	v_min_u32_e32 v38, v38, v54
	v_max_u32_e32 v54, v56, v44
	v_min_u32_e32 v44, v56, v44
	v_max_u32_e32 v56, v40, v53
	v_min_u32_e32 v40, v40, v53
	v_max_u32_e32 v53, v37, v31
	v_min_u32_e32 v37, v37, v31
	v_max_u32_e32 v60, v43, v20
	v_min_u32_e32 v43, v43, v20
	v_mov_b32_e32 v31, v36
	v_mov_b32_e32 v20, v25
	v_mov_b32_e32 v21, v34
	v_pk_add_f32 v[20:21], v[30:31], v[20:21]
	v_min_u32_e32 v61, v39, v59
	v_not_b32_e32 v31, v21
	v_or_b32_e32 v34, 0x80000000, v21
	v_cmp_gt_i32_e32 vcc, 0, v21
	v_min_u32_e32 v62, v55, v42
	v_min_u32_e32 v63, v58, v57
	v_cndmask_b32_e32 v21, v34, v31, vcc
	v_and_b32_e32 v21, 0xffffff00, v21
	v_or_b32_e32 v31, 0xcc, v21
	v_not_b32_e32 v21, v20
	v_or_b32_e32 v34, 0x80000000, v20
	v_cmp_gt_i32_e32 vcc, 0, v20
	v_pk_add_f32 v[18:19], v[30:31], v[18:19] op_sel_hi:[0,1]
	v_min_u32_e32 v64, v35, v38
	v_cndmask_b32_e32 v20, v34, v21, vcc
	v_and_b32_e32 v20, 0xffffff00, v20
	v_or_b32_e32 v34, 0xbf, v20
	v_not_b32_e32 v20, v19
	v_or_b32_e32 v21, 0x80000000, v19
	v_cmp_gt_i32_e32 vcc, 0, v19
	v_min_u32_e32 v65, v54, v56
	v_min_u32_e32 v66, v44, v40
	v_cndmask_b32_e32 v19, v21, v20, vcc
	v_and_b32_e32 v19, 0xffffff00, v19
	v_or_b32_e32 v30, 0xbe, v19
	v_not_b32_e32 v19, v18
	v_or_b32_e32 v20, 0x80000000, v18
	v_cmp_gt_i32_e32 vcc, 0, v18
	v_min_u32_e32 v67, v53, v60
; DI unsigned enc_key(float s) { const unsigned u = __float_as_uint(s); return (u & 0x80000000u) ? ~u : (u | 0x80000000u); }
; DI void phase_peer_q(const Params& p, char* smem) {
;     ...
;       for (int gi = 0; gi < 4; ++gi) {
;         unsigned X[16];
; #pragma unroll
;         for (int i = 0; i < 16; ++i) {
;           const int c = gi * 16 + i;
;           X[i] = (c < CT.n) ? ((enc_key(s1[CT.i[c]] + s2[CT.j[c]]) & ~255u) | (unsigned)(255 - (CT.i[c] * 16 + CT.j[c]))) : 0u;
;         }
;         sort16_desc(X);
;         if (gi == 0) {
; #pragma unroll
;           for (int i = 0; i < 16; ++i) B[i] = X[i];
;         } else merge16_desc(B, X);
	v_min_u32_e32 v68, v37, v43
	v_cndmask_b32_e32 v18, v20, v19, vcc
	v_and_b32_e32 v18, 0xffffff00, v18
	v_or_b32_e32 v36, 0xbd, v18
	v_pk_add_f32 v[18:19], v[32:33], v[24:25] op_sel_hi:[0,1]
	v_not_b32_e32 v20, v19
	v_or_b32_e32 v21, 0x80000000, v19
	v_cmp_gt_i32_e32 vcc, 0, v19
	s_nop 1
	v_cndmask_b32_e32 v19, v21, v20, vcc
	v_and_b32_e32 v19, 0xffffff00, v19
	v_or_b32_e32 v32, 0xaf, v19
	v_not_b32_e32 v19, v18
	v_or_b32_e32 v20, 0x80000000, v18
	v_cmp_gt_i32_e32 vcc, 0, v18
	s_nop 1
	v_cndmask_b32_e32 v18, v20, v19, vcc
	v_and_b32_e32 v18, 0xffffff00, v18
	v_or_b32_e32 v69, 0xae, v18
	v_pk_add_f32 v[18:19], v[26:27], v[24:25] op_sel_hi:[0,1]
	v_not_b32_e32 v20, v19
	v_or_b32_e32 v21, 0x80000000, v19
	v_cmp_gt_i32_e32 vcc, 0, v19
	s_nop 1
	v_cndmask_b32_e32 v19, v21, v20, vcc
	v_and_b32_e32 v19, 0xffffff00, v19
	v_or_b32_e32 v26, 0x9f, v19
	v_not_b32_e32 v19, v18
	v_or_b32_e32 v20, 0x80000000, v18
	v_cmp_gt_i32_e32 vcc, 0, v18
	s_nop 1
	v_cndmask_b32_e32 v18, v20, v19, vcc
	v_and_b32_e32 v18, 0xffffff00, v18
	v_or_b32_e32 v70, 0x9e, v18
	v_pk_add_f32 v[18:19], v[28:29], v[24:25] op_sel_hi:[0,1]
	v_not_b32_e32 v20, v19
	v_or_b32_e32 v21, 0x80000000, v19
	v_cmp_gt_i32_e32 vcc, 0, v19
	s_nop 1
	v_cndmask_b32_e32 v19, v21, v20, vcc
	v_not_b32_e32 v20, v18
	v_or_b32_e32 v21, 0x80000000, v18
	v_cmp_gt_i32_e32 vcc, 0, v18
	v_and_b32_e32 v19, 0xffffff00, v19
	v_or_b32_e32 v19, 0x8f, v19
	v_cndmask_b32_e32 v18, v21, v20, vcc
	v_and_b32_e32 v18, 0xffffff00, v18
	v_or_b32_e32 v24, 0x8e, v18
	v_xor_b32_e32 v18, -1, v49
	v_cmp_gt_i32_e32 vcc, 0, v15
	v_xor_b32_e32 v20, -1, v50
	v_min_u32_e32 v49, v32, v69
	v_cndmask_b32_e32 v21, v18, v52, vcc
	v_cmp_gt_i32_e32 vcc, 0, v14
	v_mov_b32_e32 v18, v25
	v_max_u32_e32 v32, v32, v69
	v_cndmask_b32_e32 v20, v20, v51, vcc
	v_pk_add_f32 v[20:21], v[18:19], v[20:21] op_sel_hi:[0,1]
	v_not_b32_e32 v25, v20
	v_or_b32_e32 v28, 0x80000000, v20
	v_cmp_gt_i32_e32 vcc, 0, v20
	s_nop 1
	v_cndmask_b32_e32 v20, v28, v25, vcc
	v_and_b32_e32 v20, 0xffffff00, v20
	v_or_b32_e32 v25, 0x7f, v20
	v_not_b32_e32 v20, v21
	v_or_b32_e32 v28, 0x80000000, v21
	v_cmp_gt_i32_e32 vcc, 0, v21
	s_nop 1
	v_cndmask_b32_e32 v20, v28, v20, vcc
	v_and_b32_e32 v20, 0xffffff00, v20
	v_or_b32_e32 v28, 0x6f, v20
	v_xor_b32_e32 v20, -1, v45
	v_cmp_gt_i32_e32 vcc, 0, v17
	v_xor_b32_e32 v45, -1, v46
	v_min_u32_e32 v72, v28, v25
	v_cndmask_b32_e32 v21, v20, v48, vcc
	v_cmp_gt_i32_e32 vcc, 0, v16
	v_max_u32_e32 v48, v70, v26
	v_min_u32_e32 v26, v70, v26
	v_cndmask_b32_e32 v20, v45, v47, vcc
	v_pk_add_f32 v[20:21], v[18:19], v[20:21] op_sel_hi:[0,1]
	v_not_b32_e32 v45, v20
	v_or_b32_e32 v46, 0x80000000, v20
	v_cmp_gt_i32_e32 vcc, 0, v20
	v_min_u32_e32 v50, v48, v49
	v_min_u32_e32 v51, v26, v32
	v_cndmask_b32_e32 v20, v46, v45, vcc
	v_and_b32_e32 v20, 0xffffff00, v20
	v_or_b32_e32 v45, 0x5f, v20
	v_not_b32_e32 v20, v21
	v_or_b32_e32 v46, 0x80000000, v21
	v_cmp_gt_i32_e32 vcc, 0, v21
	v_min_u32_e32 v21, v36, v30
	v_max_u32_e32 v30, v36, v30
	v_cndmask_b32_e32 v20, v46, v20, vcc
	v_and_b32_e32 v20, 0xffffff00, v20
	v_or_b32_e32 v46, 0x4f, v20
	v_max_u32_e32 v20, v31, v34
	v_min_u32_e32 v31, v31, v34
	v_max_u32_e32 v47, v20, v21
	v_max_u32_e32 v34, v31, v30
	v_min_u32_e32 v20, v20, v21
	v_min_u32_e32 v21, v31, v30
	v_max_u32_e32 v36, v47, v34
	v_min_u32_e32 v52, v50, v51
	v_max_u32_e32 v30, v20, v21
	v_min_u32_e32 v34, v47, v34
	v_max_u32_e32 v47, v50, v51
	v_min_u32_e32 v51, v20, v21
	v_xor_b32_e32 v20, -1, v27
	v_cmp_gt_i32_e32 vcc, 0, v11
	v_xor_b32_e32 v27, -1, v29
	v_max_u32_e32 v31, v48, v49
	v_cndmask_b32_e32 v21, v20, v41, vcc
	v_cmp_gt_i32_e32 vcc, 0, v10
	v_max_u32_e32 v26, v26, v32
	v_min_u32_e32 v32, v31, v26
	v_cndmask_b32_e32 v20, v27, v33, vcc
	v_pk_add_f32 v[20:21], v[18:19], v[20:21] op_sel_hi:[0,1]
	v_not_b32_e32 v27, v20
	v_or_b32_e32 v29, 0x80000000, v20
	v_cmp_gt_i32_e32 vcc, 0, v20
	v_max_u32_e32 v26, v31, v26
	v_max_u32_e32 v69, v36, v52
	v_cndmask_b32_e32 v20, v29, v27, vcc
	v_not_b32_e32 v27, v21
	v_or_b32_e32 v29, 0x80000000, v21
	v_cmp_gt_i32_e32 vcc, 0, v21
	v_and_or_b32 v20, v20, s66, 63
	v_max_u32_e32 v48, v30, v32
	v_cndmask_b32_e32 v21, v29, v27, vcc
	v_and_or_b32 v21, v21, s66, 47
	v_max_u32_e32 v27, v21, v20
	v_min_u32_e32 v29, v45, v46
	v_min_u32_e32 v20, v21, v20
	v_max_u32_e32 v21, v45, v46
	v_max_u32_e32 v46, v19, v24
	v_min_u32_e32 v19, v19, v24
	v_max_u32_e32 v24, v28, v25
	v_max_u32_e32 v33, v27, v29
	v_max_u32_e32 v41, v20, v21
	v_min_u32_e32 v73, v46, v72
	v_min_u32_e32 v25, v19, v24
	v_min_u32_e32 v27, v27, v29
	v_min_u32_e32 v20, v20, v21
	v_max_u32_e32 v29, v46, v72
	v_max_u32_e32 v19, v19, v24
	v_max_u32_e32 v45, v33, v41
	v_min_u32_e32 v28, v73, v25
	v_max_u32_e32 v21, v27, v20
	v_min_u32_e32 v24, v29, v19
	v_min_u32_e32 v33, v33, v41
	v_max_u32_e32 v25, v73, v25
	v_min_u32_e32 v20, v27, v20
	v_max_u32_e32 v19, v29, v19
	v_max_u32_e32 v50, v34, v47
	v_max_u32_e32 v31, v51, v26
	v_min_u32_e32 v74, v45, v28
	v_min_u32_e32 v46, v21, v24
	v_min_u32_e32 v41, v33, v25
	v_min_u32_e32 v27, v20, v19
	v_min_u32_e32 v36, v36, v52
	v_min_u32_e32 v30, v30, v32
	v_min_u32_e32 v34, v34, v47
	v_min_u32_e32 v26, v51, v26
	v_max_u32_e32 v28, v45, v28
	v_max_u32_e32 v21, v21, v24
	v_max_u32_e32 v25, v33, v25
	v_max_u32_e32 v19, v20, v19
	v_max_u32_e32 v49, v69, v48
	v_max_u32_e32 v70, v50, v31
	v_min_u32_e32 v72, v74, v46
	v_min_u32_e32 v29, v41, v27
	v_max_u32_e32 v32, v36, v30
	v_max_u32_e32 v47, v34, v26
	v_min_u32_e32 v24, v28, v21
	v_min_u32_e32 v20, v25, v19
	v_min_u32_e32 v48, v69, v48
	v_min_u32_e32 v31, v50, v31
	v_max_u32_e32 v46, v74, v46
	v_max_u32_e32 v27, v41, v27
	v_min_u32_e32 v30, v36, v30
	v_min_u32_e32 v26, v34, v26
; DI unsigned enc_key(float s) { const unsigned u = __float_as_uint(s); return (u & 0x80000000u) ? ~u : (u | 0x80000000u); }
; DI void merge16_desc(unsigned (&R)[16], const unsigned (&X)[16]) {
; #pragma unroll
;   for (int i = 0; i < 16; ++i) R[i] = R[i] > X[15 - i] ? R[i] : X[15 - i];
;   constexpr int JS[4] = {8, 4, 2, 1};
; #pragma unroll
;   for (int s = 0; s < 4; ++s) {
; #pragma unroll
;     for (int i = 0; i < 16; ++i) {
;       const int l = i ^ JS[s];
;       if (l > i) cswap(R[i], R[l]);
;     }
;   }
; }
; DI void phase_peer_q(const Params& p, char* smem) {
;     ...
;       for (int gi = 0; gi < 4; ++gi) {
;         unsigned X[16];
; #pragma unroll
;         for (int i = 0; i < 16; ++i) {
;           const int c = gi * 16 + i;
;           X[i] = (c < CT.n) ? ((enc_key(s1[CT.i[c]] + s2[CT.j[c]]) & ~255u) | (unsigned)(255 - (CT.i[c] * 16 + CT.j[c]))) : 0u;
;         }
;         sort16_desc(X);
;         if (gi == 0) {
; #pragma unroll
;           for (int i = 0; i < 16; ++i) B[i] = X[i];
;         } else merge16_desc(B, X);
	v_max_u32_e32 v21, v28, v21
	v_max_u32_e32 v19, v25, v19
	v_max_u32_e32 v71, v49, v70
	v_min_u32_e32 v73, v72, v29
	v_max_u32_e32 v51, v32, v47
	v_min_u32_e32 v33, v24, v20
	v_max_u32_e32 v50, v48, v31
	v_min_u32_e32 v41, v46, v27
	v_max_u32_e32 v34, v30, v26
	v_min_u32_e32 v25, v21, v19
	v_min_u32_e32 v75, v71, v73
	v_min_u32_e32 v45, v51, v33
	v_min_u32_e32 v69, v50, v41
	v_min_u32_e32 v28, v34, v25
	v_min_u32_e32 v52, v75, v45
	v_min_u32_e32 v36, v69, v28
	v_min_u32_e32 v49, v49, v70
	v_max_u32_e32 v29, v72, v29
	v_min_u32_e32 v32, v32, v47
	v_max_u32_e32 v20, v24, v20
	v_min_u32_e32 v31, v48, v31
	v_max_u32_e32 v27, v46, v27
	v_min_u32_e32 v26, v30, v26
	v_max_u32_e32 v19, v21, v19
	v_max_u32_e32 v45, v75, v45
	v_max_u32_e32 v28, v69, v28
	v_min_u32_e32 v74, v52, v36
	v_min_u32_e32 v70, v49, v29
	v_min_u32_e32 v24, v32, v20
	v_min_u32_e32 v46, v31, v27
	v_min_u32_e32 v21, v26, v19
	v_max_u32_e32 v36, v52, v36
	v_min_u32_e32 v52, v45, v28
	v_max_u32_e32 v28, v45, v28
	v_max_u32_e32 v45, v71, v73
	v_max_u32_e32 v33, v51, v33
	v_max_u32_e32 v41, v50, v41
	v_max_u32_e32 v25, v34, v25
	v_max_u32_e32 v29, v49, v29
	v_max_u32_e32 v20, v32, v20
	v_max_u32_e32 v27, v31, v27
	v_max_u32_e32 v19, v26, v19
	v_min_u32_e32 v47, v70, v24
	v_min_u32_e32 v30, v46, v21
	v_max_u32_e32 v24, v70, v24
	v_max_u32_e32 v21, v46, v21
	v_min_u32_e32 v51, v45, v33
	v_min_u32_e32 v34, v41, v25
	v_min_u32_e32 v32, v29, v20
	v_min_u32_e32 v26, v27, v19
	v_max_u32_e32 v33, v45, v33
	v_max_u32_e32 v25, v41, v25
	v_max_u32_e32 v20, v29, v20
	v_max_u32_e32 v19, v27, v19
	v_min_u32_e32 v48, v47, v30
	v_max_u32_e32 v30, v47, v30
	v_min_u32_e32 v46, v24, v21
	v_max_u32_e32 v21, v24, v21
	v_min_u32_e32 v50, v51, v34
	v_min_u32_e32 v31, v32, v26
	v_max_u32_e32 v34, v51, v34
	v_max_u32_e32 v26, v32, v26
	v_min_u32_e32 v41, v33, v25
	v_min_u32_e32 v27, v20, v19
	v_max_u32_e32 v25, v33, v25
	v_max_u32_e32 v19, v20, v19
	v_min_u32_e32 v72, v74, v48
	v_min_u32_e32 v47, v36, v30
	v_min_u32_e32 v69, v52, v46
	v_min_u32_e32 v24, v28, v21
	v_min_u32_e32 v49, v50, v31
	v_min_u32_e32 v32, v34, v26
	v_min_u32_e32 v29, v41, v27
	v_min_u32_e32 v20, v25, v19
	v_max3_u32 v33, v39, v59, v72
	v_max3_u32 v39, v61, v74, v48
	v_max3_u32 v42, v55, v42, v47
	v_max3_u32 v30, v62, v36, v30
	v_max3_u32 v36, v58, v57, v69
	v_max3_u32 v45, v63, v52, v46
	v_max3_u32 v24, v35, v38, v24
	v_max3_u32 v21, v64, v28, v21
	v_max3_u32 v28, v54, v56, v49
	v_max3_u32 v31, v65, v50, v31
	v_max3_u32 v32, v44, v40, v32
	v_max3_u32 v26, v66, v34, v26
	v_max3_u32 v29, v53, v60, v29
	v_max3_u32 v27, v67, v41, v27
	v_max3_u32 v20, v37, v43, v20
	v_max3_u32 v19, v68, v25, v19
	v_max_u32_e32 v25, v33, v28
	v_min_u32_e32 v28, v33, v28
	v_max_u32_e32 v33, v39, v31
	v_min_u32_e32 v31, v39, v31
	v_max_u32_e32 v34, v42, v32
	v_min_u32_e32 v32, v42, v32
	v_max_u32_e32 v35, v30, v26
	v_min_u32_e32 v26, v30, v26
	v_max_u32_e32 v30, v36, v29
	v_min_u32_e32 v29, v36, v29
	v_max_u32_e32 v36, v45, v27
	v_min_u32_e32 v27, v45, v27
	v_max_u32_e32 v37, v24, v20
	v_min_u32_e32 v20, v24, v20
	v_max_u32_e32 v24, v21, v19
	v_min_u32_e32 v19, v21, v19
	v_max_u32_e32 v21, v25, v30
	v_min_u32_e32 v25, v25, v30
	v_max_u32_e32 v30, v33, v36
	v_min_u32_e32 v33, v33, v36
	v_max_u32_e32 v36, v34, v37
	v_min_u32_e32 v34, v34, v37
	v_max_u32_e32 v37, v35, v24
	v_min_u32_e32 v24, v35, v24
	v_max_u32_e32 v35, v28, v29
	v_min_u32_e32 v28, v28, v29
	v_max_u32_e32 v29, v31, v27
	v_min_u32_e32 v27, v31, v27
	v_max_u32_e32 v31, v32, v20
	v_min_u32_e32 v20, v32, v20
	v_max_u32_e32 v32, v26, v19
	v_min_u32_e32 v19, v26, v19
	v_max_u32_e32 v26, v21, v36
	v_min_u32_e32 v21, v21, v36
	v_max_u32_e32 v36, v30, v37
	v_min_u32_e32 v30, v30, v37
	v_max_u32_e32 v37, v25, v34
	v_min_u32_e32 v25, v25, v34
	v_max_u32_e32 v34, v33, v24
	v_min_u32_e32 v24, v33, v24
	v_max_u32_e32 v33, v35, v31
	v_min_u32_e32 v31, v35, v31
	v_max_u32_e32 v35, v29, v32
	v_min_u32_e32 v29, v29, v32
	v_max_u32_e32 v32, v28, v20
	v_min_u32_e32 v20, v28, v20
	v_max_u32_e32 v28, v27, v19
	v_min_u32_e32 v27, v27, v19
	v_pk_add_f32 v[18:19], v[22:23], v[18:19] op_sel_hi:[1,0]
	v_max_u32_e32 v38, v26, v36
	v_not_b32_e32 v22, v19
	v_or_b32_e32 v23, 0x80000000, v19
	v_cmp_gt_i32_e32 vcc, 0, v19
	v_min_u32_e32 v26, v26, v36
	v_max_u32_e32 v36, v21, v30
	v_cndmask_b32_e32 v19, v23, v22, vcc
	v_not_b32_e32 v22, v18
	v_or_b32_e32 v23, 0x80000000, v18
	v_cmp_gt_i32_e32 vcc, 0, v18
	v_and_or_b32 v19, v19, s66, 31
	v_min_u32_e32 v21, v21, v30
	v_cndmask_b32_e32 v18, v23, v22, vcc
	v_and_or_b32 v18, v18, s66, 15
	v_max_u32_e32 v30, v37, v34
	v_min_u32_e32 v34, v37, v34
	v_max_u32_e32 v37, v25, v24
	v_min_u32_e32 v24, v25, v24
	v_max_u32_e32 v25, v33, v35
	v_min_u32_e32 v33, v33, v35
	v_max_u32_e32 v35, v31, v29
	v_min_u32_e32 v29, v31, v29
	v_max_u32_e32 v31, v32, v28
	v_min_u32_e32 v28, v32, v28
	v_min_u32_e32 v32, v20, v27
	v_min_u32_e32 v41, v19, v18
	v_max3_u32 v20, v20, v27, v41
	v_max3_u32 v18, v32, v19, v18
	v_min_u32_e32 v22, v38, v25
	v_min_u32_e32 v23, v30, v31
	v_min_u32_e32 v40, v36, v35
	v_min_u32_e32 v27, v37, v20
	v_min_u32_e32 v43, v26, v33
	v_min_u32_e32 v44, v34, v28
	v_min_u32_e32 v46, v21, v29
	v_min_u32_e32 v19, v24, v18
	v_min_u32_e32 v39, v22, v23
	v_min_u32_e32 v41, v40, v27
	v_min_u32_e32 v45, v43, v44
	v_min_u32_e32 v32, v46, v19
	v_min_u32_e32 v42, v39, v41
	v_min_u32_e32 v47, v45, v32
	v_max_u32_e32 v39, v39, v41
	v_max_u32_e32 v32, v45, v32
	v_min_u32_e32 v41, v39, v32
	v_max_u32_e32 v39, v39, v32
	v_max_u32_e32 v22, v22, v23
	v_max_u32_e32 v23, v40, v27
	v_max_u32_e32 v32, v43, v44
	v_max_u32_e32 v19, v46, v19
	v_min_u32_e32 v27, v22, v23
	v_min_u32_e32 v40, v32, v19
; DI float dec_key(unsigned k) { const unsigned u = (k & 0x80000000u) ? (k & 0x7fffffffu) : ~k; return __uint_as_float(u); }
; DI void phase_peer_q(const Params& p, char* smem) {
;     ...
;       float e[16], sum = 0.f;
;       const float s0 = dec_key(B[0] & ~255u);
; #pragma unroll
;       for (int i = 0; i < 16; ++i) { e[i] = __expf(dec_key(B[i] & ~255u) - s0); sum += e[i]; }
	v_max_u32_e32 v22, v22, v23
	v_max_u32_e32 v19, v32, v19
	v_min_u32_e32 v51, v22, v19
	v_max_u32_e32 v53, v22, v19
	v_max_u32_e32 v19, v38, v25
	v_max_u32_e32 v22, v30, v31
	v_max_u32_e32 v25, v36, v35
	v_max_u32_e32 v20, v37, v20
	v_max_u32_e32 v26, v26, v33
	v_max_u32_e32 v28, v34, v28
	v_max_u32_e32 v21, v21, v29
	v_max_u32_e32 v18, v24, v18
	v_min_u32_e32 v43, v27, v40
	v_max_u32_e32 v40, v27, v40
	v_min_u32_e32 v23, v19, v22
	v_min_u32_e32 v27, v25, v20
	v_min_u32_e32 v31, v26, v28
	v_min_u32_e32 v24, v21, v18
	v_min_u32_e32 v30, v23, v27
	v_min_u32_e32 v29, v31, v24
	v_max_u32_e32 v23, v23, v27
	v_max_u32_e32 v24, v31, v24
	v_min_u32_e32 v55, v23, v24
	v_max_u32_e32 v57, v23, v24
	v_max_u32_e32 v19, v19, v22
	v_max_u32_e32 v20, v25, v20
	v_max_u32_e32 v23, v26, v28
	v_max_u32_e32 v18, v21, v18
	v_min_u32_e32 v22, v19, v20
	v_min_u32_e32 v21, v23, v18
	v_max_u32_e32 v19, v19, v20
	v_max_u32_e32 v18, v23, v18
	v_min_u32_e32 v62, v19, v18
	v_max_u32_e32 v61, v22, v21
	v_max_u32_e32 v63, v19, v18
	v_and_b32_e32 v18, 0x7fffff00, v62
	v_bitop3_b32 v19, v62, s76, v62 bitop3:0xcf
	v_cmp_gt_i32_e32 vcc, 0, v62
	v_min_u32_e32 v59, v22, v21
	v_bitop3_b32 v20, v61, s76, v61 bitop3:0xcf
	v_cndmask_b32_e32 v18, v19, v18, vcc
	v_and_b32_e32 v19, 0x7fffff00, v61
	v_cmp_gt_i32_e32 vcc, 0, v61
	v_bitop3_b32 v21, v59, s76, v59 bitop3:0xcf
	v_bitop3_b32 v22, v57, s76, v57 bitop3:0xcf
	v_cndmask_b32_e32 v19, v20, v19, vcc
	v_and_b32_e32 v20, 0x7fffff00, v59
	v_cmp_gt_i32_e32 vcc, 0, v59
	v_min_u32_e32 v36, v30, v29
	v_max_u32_e32 v29, v30, v29
	v_cndmask_b32_e32 v20, v21, v20, vcc
	v_and_b32_e32 v21, 0x7fffff00, v57
	v_cmp_gt_i32_e32 vcc, 0, v57
	v_bitop3_b32 v23, v55, s76, v55 bitop3:0xcf
	v_bitop3_b32 v24, v29, s76, v29 bitop3:0xcf
	v_cndmask_b32_e32 v21, v22, v21, vcc
	v_and_b32_e32 v22, 0x7fffff00, v55
	v_cmp_gt_i32_e32 vcc, 0, v55
	v_bitop3_b32 v25, v36, s76, v36 bitop3:0xcf
	v_bitop3_b32 v26, v53, s76, v53 bitop3:0xcf
	v_cndmask_b32_e32 v22, v23, v22, vcc
	v_and_b32_e32 v23, 0x7fffff00, v29
	v_cmp_gt_i32_e32 vcc, 0, v29
	v_bitop3_b32 v27, v51, s76, v51 bitop3:0xcf
	v_min_u32_e32 v48, v42, v47
	v_cndmask_b32_e32 v23, v24, v23, vcc
	v_and_b32_e32 v24, 0x7fffff00, v36
	v_cmp_gt_i32_e32 vcc, 0, v36
	v_max_u32_e32 v42, v42, v47
	v_and_b32_e32 v31, 0x7fffff00, v48
	v_cndmask_b32_e32 v24, v25, v24, vcc
	v_and_b32_e32 v25, 0x7fffff00, v53
	v_cmp_gt_i32_e32 vcc, 0, v53
	v_and_b32_e32 v30, 0x7fffff00, v63
	v_not_b32_e32 v37, v36
	v_cndmask_b32_e32 v25, v26, v25, vcc
	v_and_b32_e32 v26, 0x7fffff00, v51
	v_cmp_gt_i32_e32 vcc, 0, v51
	v_not_b32_e32 v38, v29
	v_not_b32_e32 v56, v55
	v_cndmask_b32_e32 v28, v27, v26, vcc
	v_and_b32_e32 v26, 0x7fffff00, v40
	v_bitop3_b32 v27, v40, s76, v40 bitop3:0xcf
	v_cmp_gt_i32_e32 vcc, 0, v40
	v_not_b32_e32 v58, v57
	v_not_b32_e32 v60, v59
	v_cndmask_b32_e32 v64, v27, v26, vcc
	v_and_b32_e32 v26, 0x7fffff00, v43
	v_bitop3_b32 v27, v43, s76, v43 bitop3:0xcf
	v_cmp_gt_i32_e32 vcc, 0, v43
	v_lshrrev_b32_e32 v60, 2, v60
	v_lshrrev_b32_e32 v58, 2, v58
	v_cndmask_b32_e32 v65, v27, v26, vcc
	v_and_b32_e32 v26, 0x7fffff00, v39
	v_bitop3_b32 v27, v39, s76, v39 bitop3:0xcf
	v_cmp_gt_i32_e32 vcc, 0, v39
	v_lshrrev_b32_e32 v56, 2, v56
	v_lshrrev_b32_e32 v38, 2, v38
	v_cndmask_b32_e32 v66, v27, v26, vcc
	v_and_b32_e32 v26, 0x7fffff00, v41
	v_bitop3_b32 v27, v41, s76, v41 bitop3:0xcf
	v_cmp_gt_i32_e32 vcc, 0, v41
	v_lshrrev_b32_e32 v37, 2, v37
	v_and_b32_e32 v60, 60, v60
	v_cndmask_b32_e32 v67, v27, v26, vcc
	v_and_b32_e32 v26, 0x7fffff00, v42
	v_bitop3_b32 v27, v42, s76, v42 bitop3:0xcf
	v_cmp_gt_i32_e32 vcc, 0, v42
	v_bitop3_b32 v59, v59, 15, v59 bitop3:0xc
	v_and_b32_e32 v58, 60, v58
	v_cndmask_b32_e32 v68, v27, v26, vcc
	v_and_b32_e32 v27, 0xffffff00, v48
	v_and_b32_e32 v26, 0xffffff00, v63
	v_xor_b32_e32 v27, -1, v27
	v_cmp_gt_i32_e32 vcc, 0, v48
	v_xor_b32_e32 v26, -1, v26
	v_bitop3_b32 v57, v57, 15, v57 bitop3:0xc
	v_cndmask_b32_e32 v69, v27, v31, vcc
	v_cmp_gt_i32_e32 vcc, 0, v63
	v_and_b32_e32 v56, 60, v56
	v_bitop3_b32 v55, v55, 15, v55 bitop3:0xc
	v_cndmask_b32_e32 v70, v26, v30, vcc
	v_sub_f32_e32 v18, v18, v70
	v_mul_f32_e32 v18, 0x3fb8aa3b, v18
	v_sub_f32_e32 v26, v70, v70
	v_exp_f32_e32 v33, v18
	v_sub_f32_e32 v18, v19, v70
	v_sub_f32_e32 v19, v21, v70
	v_mul_f32_e32 v26, 0x3fb8aa3b, v26
	v_mul_f32_e32 v19, 0x3fb8aa3b, v19
	v_exp_f32_e32 v32, v26
	v_exp_f32_e32 v26, v19
	v_sub_f32_e32 v19, v22, v70
	v_mul_f32_e32 v19, 0x3fb8aa3b, v19
	v_exp_f32_e32 v27, v19
	v_sub_f32_e32 v19, v23, v70
	v_mul_f32_e32 v18, 0x3fb8aa3b, v18
	v_mul_f32_e32 v19, 0x3fb8aa3b, v19
	v_exp_f32_e32 v34, v18
	v_sub_f32_e32 v18, v20, v70
	v_exp_f32_e32 v30, v19
	v_sub_f32_e32 v19, v24, v70
	v_mul_f32_e32 v18, 0x3fb8aa3b, v18
	v_mul_f32_e32 v19, 0x3fb8aa3b, v19
	v_exp_f32_e32 v35, v18
	v_exp_f32_e32 v31, v19
	v_sub_f32_e32 v19, v25, v70
	v_add_f32_e32 v18, 0, v32
	v_mul_f32_e32 v19, 0x3fb8aa3b, v19
	v_add_f32_e32 v18, v33, v18
	v_exp_f32_e32 v22, v19
	v_sub_f32_e32 v19, v28, v70
	v_add_f32_e32 v18, v34, v18
	v_mul_f32_e32 v19, 0x3fb8aa3b, v19
	v_add_f32_e32 v18, v35, v18
	v_exp_f32_e32 v23, v19
	v_sub_f32_e32 v19, v64, v70
	v_add_f32_e32 v18, v26, v18
	v_mul_f32_e32 v19, 0x3fb8aa3b, v19
	v_add_f32_e32 v18, v27, v18
	v_exp_f32_e32 v24, v19
	v_sub_f32_e32 v19, v65, v70
	v_add_f32_e32 v18, v30, v18
	v_mul_f32_e32 v19, 0x3fb8aa3b, v19
	v_add_f32_e32 v18, v31, v18
	v_exp_f32_e32 v25, v19
	v_add_f32_e32 v18, v22, v18
	v_add_f32_e32 v18, v23, v18
	v_add_f32_e32 v18, v24, v18
	v_add_f32_e32 v28, v25, v18
	v_sub_f32_e32 v18, v66, v70
	v_mul_f32_e32 v18, 0x3fb8aa3b, v18
	v_sub_f32_e32 v19, v67, v70
	v_exp_f32_e32 v18, v18
	v_mul_f32_e32 v19, 0x3fb8aa3b, v19
; DI float dec_key(unsigned k) { const unsigned u = (k & 0x80000000u) ? (k & 0x7fffffffu) : ~k; return __uint_as_float(u); }
; DI void phase_peer_q(const Params& p, char* smem) {
;     ...
;       float e[16], sum = 0.f;
;       const float s0 = dec_key(B[0] & ~255u);
; #pragma unroll
;       for (int i = 0; i < 16; ++i) { e[i] = __expf(dec_key(B[i] & ~255u) - s0); sum += e[i]; }
;       const float inv = 1.f / sum;
;       int ids[16];
; #pragma unroll
;       for (int i = 0; i < 16; ++i) {
;         const int flat = 255 - (int)(B[i] & 255u);
;         const int i1 = 127 - (int)(xch[(tok * 2 + 0) * 16 + (flat >> 4)] & 127u);
;         const int i2 = 127 - (int)(xch[(tok * 2 + 1) * 16 + (flat & 15)] & 127u);
	v_sub_f32_e32 v20, v68, v70
	v_exp_f32_e32 v19, v19
	v_mul_f32_e32 v20, 0x3fb8aa3b, v20
	v_sub_f32_e32 v21, v69, v70
	v_exp_f32_e32 v20, v20
	v_mul_f32_e32 v21, 0x3fb8aa3b, v21
	v_exp_f32_e32 v21, v21
	v_add_f32_e32 v28, v18, v28
	v_add_f32_e32 v28, v19, v28
	v_add_f32_e32 v28, v20, v28
	v_add_f32_e32 v28, v21, v28
	v_div_scale_f32 v64, s[0:1], v28, v28, 1.0
	v_rcp_f32_e32 v65, v64
	v_not_b32_e32 v66, v61
	v_not_b32_e32 v67, v62
	v_not_b32_e32 v68, v63
	v_fma_f32 v69, -v64, v65, 1.0
	v_fmac_f32_e32 v65, v69, v65
	v_div_scale_f32 v69, vcc, 1.0, v28, 1.0
	v_mul_f32_e32 v70, v69, v65
	v_fma_f32 v71, -v64, v70, v69
	v_fmac_f32_e32 v70, v71, v65
	v_fma_f32 v64, -v64, v70, v69
	v_div_fmas_f32 v64, v64, v65, v70
	v_div_fixup_f32 v28, v64, v28, 1.0
	v_lshrrev_b32_e32 v64, 2, v68
	v_lshrrev_b32_e32 v65, 2, v67
	v_lshrrev_b32_e32 v66, 2, v66
	v_and_b32_e32 v64, 60, v64
	v_bitop3_b32 v63, v63, 15, v63 bitop3:0xc
	v_and_b32_e32 v65, 60, v65
	v_bitop3_b32 v62, v62, 15, v62 bitop3:0xc
	v_and_b32_e32 v66, 60, v66
	v_bitop3_b32 v61, v61, 15, v61 bitop3:0xc
	v_and_b32_e32 v38, 60, v38
	v_bitop3_b32 v29, v29, 15, v29 bitop3:0xc
	v_and_b32_e32 v37, 60, v37
	v_add_u32_e32 v64, v124, v64
	v_lshl_add_u32 v63, v63, 2, v124
	v_add_u32_e32 v65, v124, v65
	v_lshl_add_u32 v62, v62, 2, v124
	v_add_u32_e32 v66, v124, v66
	v_lshl_add_u32 v61, v61, 2, v124
	v_add_u32_e32 v60, v124, v60
	v_lshl_add_u32 v59, v59, 2, v124
	v_add_u32_e32 v58, v124, v58
	v_lshl_add_u32 v57, v57, 2, v124
	v_add_u32_e32 v56, v124, v56
	v_lshl_add_u32 v55, v55, 2, v124
	v_add_u32_e32 v38, v124, v38
	v_lshl_add_u32 v29, v29, 2, v124
	v_add_u32_e32 v37, v124, v37
	v_bitop3_b32 v36, v36, 15, v36 bitop3:0xc
	ds_read_b32 v64, v64
	ds_read_b32 v63, v63 offset:64
	ds_read_b32 v65, v65
	ds_read_b32 v62, v62 offset:64
	ds_read_b32 v66, v66
	ds_read_b32 v61, v61 offset:64
	ds_read_b32 v60, v60
	ds_read_b32 v59, v59 offset:64
	v_lshl_add_u32 v36, v36, 2, v124
	ds_read_b32 v58, v58
	ds_read_b32 v57, v57 offset:64
	ds_read_b32 v56, v56
	ds_read_b32 v55, v55 offset:64
	ds_read_b32 v38, v38
	ds_read_b32 v29, v29 offset:64
	ds_read_b32 v37, v37
	ds_read_b32 v67, v36 offset:64
	v_not_b32_e32 v44, v43
	v_not_b32_e32 v46, v40
	v_not_b32_e32 v52, v51
	v_not_b32_e32 v54, v53
	s_waitcnt lgkmcnt(3)
	v_lshlrev_b32_e32 v68, 7, v38
	v_lshrrev_b32_e32 v36, 2, v54
	v_lshrrev_b32_e32 v38, 2, v52
	v_lshrrev_b32_e32 v46, 2, v46
	v_lshrrev_b32_e32 v44, 2, v44
	s_waitcnt lgkmcnt(1)
	v_lshlrev_b32_e32 v69, 7, v37
	v_and_b32_e32 v36, 60, v36
	v_bitop3_b32 v37, v53, 15, v53 bitop3:0xc
	v_and_b32_e32 v38, 60, v38
	v_bitop3_b32 v51, v51, 15, v51 bitop3:0xc
	v_and_b32_e32 v46, 60, v46
	v_bitop3_b32 v40, v40, 15, v40 bitop3:0xc
	v_and_b32_e32 v44, 60, v44
	v_add_u32_e32 v36, v124, v36
	v_lshl_add_u32 v37, v37, 2, v124
	v_add_u32_e32 v38, v124, v38
	v_lshl_add_u32 v51, v51, 2, v124
	v_add_u32_e32 v46, v124, v46
	v_lshl_add_u32 v40, v40, 2, v124
	v_add_u32_e32 v44, v124, v44
	v_bitop3_b32 v43, v43, 15, v43 bitop3:0xc
	v_lshl_add_u32 v43, v43, 2, v124
	ds_read_b32 v36, v36
	ds_read_b32 v52, v37 offset:64
	ds_read_b32 v37, v38
	ds_read_b32 v51, v51 offset:64
	ds_read_b32 v38, v46
	ds_read_b32 v46, v40 offset:64
	ds_read_b32 v40, v44
	ds_read_b32 v44, v43 offset:64
	v_not_b32_e32 v45, v41
	v_not_b32_e32 v50, v39
	v_not_b32_e32 v49, v48
	v_not_b32_e32 v47, v42
	s_waitcnt lgkmcnt(7)
	v_lshlrev_b32_e32 v53, 7, v36
	s_waitcnt lgkmcnt(3)
	v_lshlrev_b32_e32 v70, 7, v38
	v_lshrrev_b32_e32 v36, 2, v50
	v_lshrrev_b32_e32 v38, 2, v45
	v_lshlrev_b32_e32 v54, 7, v37
	s_waitcnt lgkmcnt(1)
	v_lshlrev_b32_e32 v71, 7, v40
	v_and_b32_e32 v36, 60, v36
	v_bitop3_b32 v37, v39, 15, v39 bitop3:0xc
	v_and_b32_e32 v38, 60, v38
	v_bitop3_b32 v39, v41, 15, v41 bitop3:0xc
	v_lshrrev_b32_e32 v40, 2, v47
	v_bitop3_b32 v41, v42, 15, v42 bitop3:0xc
	v_lshrrev_b32_e32 v42, 2, v49
	v_add_u32_e32 v36, v124, v36
	v_lshl_add_u32 v37, v37, 2, v124
	v_add_u32_e32 v38, v124, v38
	v_lshl_add_u32 v39, v39, 2, v124
	v_and_b32_e32 v40, 60, v40
	v_and_b32_e32 v42, 60, v42
	v_bitop3_b32 v43, v48, 15, v48 bitop3:0xc
	v_add_u32_e32 v40, v124, v40
	v_lshl_add_u32 v41, v41, 2, v124
	v_add_u32_e32 v42, v124, v42
	v_lshl_add_u32 v43, v43, 2, v124
	ds_read_b32 v36, v36
	ds_read_b32 v45, v37 offset:64
	ds_read_b32 v37, v38
	ds_read_b32 v47, v39 offset:64
	ds_read_b32 v38, v40
	ds_read_b32 v48, v41 offset:64
	ds_read_b32 v39, v42
	ds_read_b32 v49, v43 offset:64
	s_waitcnt lgkmcnt(7)
; DI void phase_peer_q(const Params& p, char* smem) {
;     ...
;       int ids[16];
; #pragma unroll
;       for (int i = 0; i < 16; ++i) {
;         const int flat = 255 - (int)(B[i] & 255u);
;         const int i1 = 127 - (int)(xch[(tok * 2 + 0) * 16 + (flat >> 4)] & 127u);
;         const int i2 = 127 - (int)(xch[(tok * 2 + 1) * 16 + (flat & 15)] & 127u);
;         ids[i] = i1 * 128 + i2;
;         e[i] *= inv;
;       }
;       int* di = sel_i + (size_t)(m0 + tok) * 128 + hd * 16;
;       float* dg = sel_g + (size_t)(m0 + tok) * 128 + hd * 16;
; #pragma unroll
;       for (int k = 0; k < 4; ++k) {
;         *(int4*)(di + 4 * k) = int4{ids[4 * k], ids[4 * k + 1], ids[4 * k + 2], ids[4 * k + 3]};
;         *(float4*)(dg + 4 * k) = float4{e[4 * k], e[4 * k + 1], e[4 * k + 2], e[4 * k + 3]};
;       }
	v_lshlrev_b32_e32 v50, 7, v36
	v_or_b32_e32 v36, s80, v0
	s_waitcnt lgkmcnt(5)
	v_lshlrev_b32_e32 v72, 7, v37
	v_ashrrev_i32_e32 v37, 31, v36
	s_lshl_b32 s0, s79, 4
	v_lshlrev_b64 v[36:37], 9, v[36:37]
	s_ashr_i32 s1, s0, 31
	v_lshlrev_b32_e32 v64, 7, v64
	v_lshlrev_b32_e32 v65, 7, v65
	s_waitcnt lgkmcnt(3)
	v_lshlrev_b32_e32 v73, 7, v38
	s_waitcnt lgkmcnt(1)
	v_lshlrev_b32_e32 v74, 7, v39
	v_lshl_add_u64 v[38:39], s[46:47], 0, v[36:37]
	s_lshl_b64 s[0:1], s[0:1], 2
	v_lshl_add_u64 v[36:37], s[48:49], 0, v[36:37]
	v_lshl_add_u64 v[40:41], v[38:39], 0, s[0:1]
	v_lshl_add_u64 v[42:43], v[36:37], 0, s[0:1]
	v_and_b32_e32 v36, 0x7f, v62
	v_and_b32_e32 v37, 0x3f80, v64
	v_and_b32_e32 v38, 0x3f80, v65
	v_and_b32_e32 v39, 0x7f, v63
	v_lshlrev_b32_e32 v66, 7, v66
	v_lshlrev_b32_e32 v60, 7, v60
	v_or_b32_e32 v36, v36, v38
	v_or_b32_e32 v38, v37, v39
	v_lshlrev_b32_e32 v58, 7, v58
	v_lshlrev_b32_e32 v56, 7, v56
	v_xor_b32_e32 v37, 0x3fff, v36
	v_xor_b32_e32 v36, 0x3fff, v38
	v_and_b32_e32 v38, 0x7f, v59
	v_and_b32_e32 v39, 0x3f80, v66
	v_and_b32_e32 v59, 0x3f80, v60
	v_and_b32_e32 v60, 0x7f, v61
	v_pk_mul_f32 v[32:33], v[32:33], v[28:29] op_sel_hi:[1,0]
	v_pk_mul_f32 v[34:35], v[34:35], v[28:29] op_sel_hi:[1,0]
	v_or_b32_e32 v38, v38, v59
	v_or_b32_e32 v59, v39, v60
	global_store_dwordx4 v[42:43], v[32:35], off
	v_xor_b32_e32 v39, 0x3fff, v38
	v_xor_b32_e32 v38, 0x3fff, v59
	v_and_b32_e32 v32, 0x7f, v55
	v_and_b32_e32 v33, 0x3f80, v58
	v_and_b32_e32 v34, 0x3f80, v56
	v_and_b32_e32 v35, 0x7f, v57
	v_or_b32_e32 v32, v32, v34
	v_or_b32_e32 v34, v33, v35
	global_store_dwordx4 v[40:41], v[36:39], off
	v_xor_b32_e32 v33, 0x3fff, v32
	v_xor_b32_e32 v32, 0x3fff, v34
	v_and_b32_e32 v34, 0x7f, v67
	v_and_b32_e32 v35, 0x3f80, v68
	v_and_b32_e32 v36, 0x3f80, v69
	v_and_b32_e32 v29, 0x7f, v29
	v_or_b32_e32 v34, v34, v36
	v_or_b32_e32 v29, v35, v29
	v_xor_b32_e32 v35, 0x3fff, v34
	v_xor_b32_e32 v34, 0x3fff, v29
	global_store_dwordx4 v[40:41], v[32:35], off offset:16
	s_nop 1
	v_pk_mul_f32 v[32:33], v[26:27], v[28:29] op_sel_hi:[1,0]
	v_pk_mul_f32 v[34:35], v[30:31], v[28:29] op_sel_hi:[1,0]
	v_and_b32_e32 v26, 0x7f, v51
	v_and_b32_e32 v29, 0x3f80, v54
	v_and_b32_e32 v27, 0x3f80, v53
	v_and_b32_e32 v30, 0x7f, v52
	v_or_b32_e32 v26, v26, v29
	v_and_b32_e32 v29, 0x3f80, v71
	v_or_b32_e32 v27, v27, v30
	v_pk_mul_f32 v[22:23], v[22:23], v[28:29] op_sel_hi:[1,0]
	v_pk_mul_f32 v[24:25], v[24:25], v[28:29] op_sel_hi:[1,0]
	global_store_dwordx4 v[42:43], v[32:35], off offset:16
	v_xor_b32_e32 v31, 0x3fff, v26
	v_xor_b32_e32 v30, 0x3fff, v27
	v_and_b32_e32 v26, 0x7f, v44
	v_and_b32_e32 v27, 0x3f80, v70
	v_and_b32_e32 v32, 0x7f, v46
	global_store_dwordx4 v[42:43], v[22:25], off offset:32
	v_or_b32_e32 v26, v26, v29
	v_or_b32_e32 v27, v27, v32
	v_and_b32_e32 v22, 0x7f, v47
	v_and_b32_e32 v23, 0x3f80, v50
	v_and_b32_e32 v24, 0x3f80, v72
	v_and_b32_e32 v25, 0x7f, v45
	v_or_b32_e32 v22, v22, v24
	v_or_b32_e32 v24, v23, v25
	v_xor_b32_e32 v33, 0x3fff, v26
	v_xor_b32_e32 v32, 0x3fff, v27
	v_xor_b32_e32 v23, 0x3fff, v22
	v_xor_b32_e32 v22, 0x3fff, v24
	s_waitcnt lgkmcnt(0)
	v_and_b32_e32 v24, 0x7f, v49
	v_and_b32_e32 v25, 0x3f80, v73
	v_and_b32_e32 v26, 0x3f80, v74
	v_and_b32_e32 v27, 0x7f, v48
	v_or_b32_e32 v24, v24, v26
	v_or_b32_e32 v26, v25, v27
	v_xor_b32_e32 v25, 0x3fff, v24
	v_xor_b32_e32 v24, 0x3fff, v26
	v_pk_mul_f32 v[18:19], v[18:19], v[28:29] op_sel_hi:[1,0]
	v_pk_mul_f32 v[20:21], v[20:21], v[28:29] op_sel_hi:[1,0]
	global_store_dwordx4 v[40:41], v[30:33], off offset:32
	global_store_dwordx4 v[40:41], v[22:25], off offset:48
	global_store_dwordx4 v[42:43], v[18:21], off offset:48
	s_branch .LBB0_396
